# attention tile: fewer waits/SALU per tile, DMA address arithmetic simplified, lookahead 3 tiles with vmcnt(4); res5 epilogue loads hoisted within each row group
# speedup vs baseline: 1.0066x; 1.0066x over previous
; __device__ __forceinline__ unsigned pk2(float lo, float hi) { f32x2 v = {lo, hi}; bf16x2_t b = __builtin_convertvector(v, bf16x2_t); return __builtin_bit_cast(unsigned, b); }
; __device__ __forceinline__ float bflo(unsigned u) { return __uint_as_float(u << 16); }
; __device__ __forceinline__ float bfhi(unsigned u) { return __uint_as_float(u & 0xffff0000u); }
;     __device__ __forceinline__ void operator()(const pg8::f32x4 (&acc)[2][2][4][2], const pg8::Unit& u, int wr, int wc, int fr, int fq) const {
;     ...
;         for (int ai = 0; ai < 2; ++ai)
; #pragma unroll
;             for (int m = 0; m < 4; ++m) { const int row = u.pm * 256 + ai * 128 + wr * 64 + m * 16 + fr;
;                 const float* rb = (row < TP ? res0 : res1) + (size_t)row * DM; bf16_t* xr = X + (size_t)row * DM; float ss = 0.f;
; #pragma unroll
;                 for (int bj = 0; bj < 2; ++bj)
; #pragma unroll
;                     for (int n = 0; n < 2; ++n) { const int col = col0 + bj * 128 + n * 16;
;                         f32x4 r;
;                         if (RES_F32) r = *(const f32x4*)(rb + col);
;                         else { const u32x2 rw = *(const u32x2*)(xr + col); r = (f32x4){bflo(rw.x), bfhi(rw.x), bflo(rw.y), bfhi(rw.y)}; }
;                         const f32x4 x = r + acc[ai][bj][m][n];
;                         ss += (x[0] * x[0] + x[1] * x[1]) + (x[2] * x[2] + x[3] * x[3]);
;                         u32x2 o; o.x = pk2(x[0], x[1]); o.y = pk2(x[2], x[3]); *(u32x2*)(xr + col) = o; }
;                 ss += __shfl_xor(ss, 16); ss += __shfl_xor(ss, 32); if (fq == 0) part[(size_t)row * 16 + u.pn * 4 + wc] = ss; }
.LBB0_532:
	v_lshl_add_u32 v146, s82, 8, v148
	v_mov_b32_e32 v145, s69
	v_mov_b32_e32 v147, s9
	v_cmp_gt_i32_e32 vcc, s73, v146
	v_lshl_or_b32 v144, s22, 8, v150
	v_xor_b32_e32 v155, 32, v154
	v_cndmask_b32_e32 v157, v145, v147, vcc
	v_mov_b32_e32 v145, s68
	v_mov_b32_e32 v147, s8
	v_cndmask_b32_e32 v156, v145, v147, vcc
	v_ashrrev_i32_e32 v147, 31, v146
	v_lshlrev_b64 v[158:159], 12, v[146:147]
	v_lshl_add_u64 v[156:157], v[156:157], 0, v[158:159]
	v_ashrrev_i32_e32 v145, 31, v144
	v_lshl_add_u64 v[160:161], v[144:145], 2, v[156:157]
	global_load_dwordx4 v[156:159], v[160:161], off
	global_load_dwordx4 v[188:191], v[160:161], off offset:64
	global_load_dwordx4 v[192:195], v[160:161], off offset:512
	global_load_dwordx4 v[196:199], v[160:161], off offset:576
	v_lshlrev_b64 v[162:163], 11, v[146:147]
	v_lshl_add_u64 v[162:163], s[66:67], 0, v[162:163]
	v_lshl_add_u64 v[162:163], v[144:145], 1, v[162:163]
	s_lshl_b32 s4, s22, 2
	s_ashr_i32 s5, s4, 31
	s_waitcnt vmcnt(3)
	v_pk_add_f32 v[158:159], v[126:127], v[158:159]
	v_pk_add_f32 v[156:157], v[124:125], v[156:157]
	v_cvt_pk_bf16_f32 v125, v158, v159
	v_cvt_pk_bf16_f32 v124, v156, v157
	global_store_dwordx2 v[162:163], v[124:125], off
	v_mul_f32_e32 v157, v157, v157
	v_mul_f32_e32 v159, v159, v159
	v_fmac_f32_e32 v157, v156, v156
	v_fmac_f32_e32 v159, v158, v158
	v_add_f32_e32 v156, v157, v159
	s_waitcnt vmcnt(3)
	v_pk_add_f32 v[190:191], v[122:123], v[190:191]
	v_pk_add_f32 v[188:189], v[120:121], v[188:189]
	v_cvt_pk_bf16_f32 v121, v190, v191
	v_cvt_pk_bf16_f32 v120, v188, v189
	global_store_dwordx2 v[162:163], v[120:121], off offset:32
	v_mul_f32_e32 v189, v189, v189
	v_mul_f32_e32 v191, v191, v191
	v_fmac_f32_e32 v189, v188, v188
	v_fmac_f32_e32 v191, v190, v190
	v_add_f32_e32 v188, v189, v191
	v_add_f32_e32 v188, v156, v188
	s_waitcnt vmcnt(3)
	v_pk_add_f32 v[194:195], v[118:119], v[194:195]
	v_pk_add_f32 v[164:165], v[116:117], v[192:193]
	v_cvt_pk_bf16_f32 v117, v194, v195
	v_cvt_pk_bf16_f32 v116, v164, v165
	global_store_dwordx2 v[162:163], v[116:117], off offset:256
	v_and_b32_e32 v117, 64, v154
	v_mul_f32_e32 v189, v165, v165
	v_mul_f32_e32 v195, v195, v195
	v_xor_b32_e32 v116, 16, v154
	v_add_u32_e32 v117, 64, v117
	v_fmac_f32_e32 v189, v164, v164
	v_fmac_f32_e32 v195, v194, v194
	v_cmp_lt_i32_e32 vcc, v116, v117
	v_add_f32_e32 v194, v189, v195
	v_add_f32_e32 v194, v188, v194
	v_cndmask_b32_e32 v116, v154, v116, vcc
	v_lshlrev_b32_e32 v116, 2, v116
	v_cmp_lt_i32_e32 vcc, v155, v117
	s_waitcnt vmcnt(3)
	v_pk_add_f32 v[198:199], v[114:115], v[198:199]
	v_pk_add_f32 v[196:197], v[112:113], v[196:197]
	v_mul_f32_e32 v113, v199, v199
	v_mul_f32_e32 v112, v197, v197
	v_fmac_f32_e32 v112, v196, v196
	v_fmac_f32_e32 v113, v198, v198
	v_add_f32_e32 v112, v112, v113
	v_add_f32_e32 v112, v194, v112
	ds_bpermute_b32 v113, v116, v112
	v_cndmask_b32_e32 v114, v154, v155, vcc
	v_lshlrev_b32_e32 v114, 2, v114
	v_cvt_pk_bf16_f32 v196, v196, v197
	v_cvt_pk_bf16_f32 v197, v198, v199
	s_waitcnt lgkmcnt(0)
	v_add_f32_e32 v112, v112, v113
	ds_bpermute_b32 v113, v114, v112
	global_store_dwordx2 v[162:163], v[196:197], off offset:288
	s_and_saveexec_b64 s[40:41], s[0:1]
	s_cbranch_execz .LBB0_534
	v_lshlrev_b64 v[196:197], 6, v[146:147]
	v_lshl_add_u64 v[196:197], s[18:19], 0, v[196:197]
	v_lshl_add_u64 v[196:197], s[4:5], 2, v[196:197]
	s_lshl_b32 s22, s70, 2
	v_lshl_add_u64 v[196:197], v[196:197], 0, s[22:23]
	s_waitcnt lgkmcnt(0)
	v_add_f32_e32 v112, v112, v113
	global_store_dword v[196:197], v112, off
.LBB0_534:
	s_or_b64 exec, exec, s[40:41]
	v_or_b32_e32 v112, 16, v146
	s_waitcnt lgkmcnt(0)
	v_mov_b32_e32 v113, s69
	v_mov_b32_e32 v115, s9
	v_cmp_gt_i32_e32 vcc, s73, v112
	s_nop 1
	v_cndmask_b32_e32 v119, v113, v115, vcc
	v_mov_b32_e32 v113, s68
	v_mov_b32_e32 v115, s8
	v_cndmask_b32_e32 v118, v113, v115, vcc
	v_ashrrev_i32_e32 v113, 31, v112
	v_lshlrev_b64 v[120:121], 12, v[112:113]
	v_lshl_add_u64 v[118:119], v[118:119], 0, v[120:121]
	v_lshl_add_u64 v[122:123], v[144:145], 2, v[118:119]
	global_load_dwordx4 v[118:121], v[122:123], off
	global_load_dwordx4 v[188:191], v[122:123], off offset:64
	global_load_dwordx4 v[192:195], v[122:123], off offset:512
	global_load_dwordx4 v[196:199], v[122:123], off offset:576
	v_lshlrev_b64 v[124:125], 11, v[112:113]
	v_lshl_add_u64 v[124:125], s[66:67], 0, v[124:125]
	v_lshl_add_u64 v[124:125], v[144:145], 1, v[124:125]
	s_waitcnt vmcnt(3)
	v_pk_add_f32 v[120:121], v[110:111], v[120:121]
	v_pk_add_f32 v[118:119], v[108:109], v[118:119]
	v_cvt_pk_bf16_f32 v109, v120, v121
	v_cvt_pk_bf16_f32 v108, v118, v119
	global_store_dwordx2 v[124:125], v[108:109], off
	v_mul_f32_e32 v115, v119, v119
	v_mul_f32_e32 v117, v121, v121
	v_fmac_f32_e32 v115, v118, v118
	v_fmac_f32_e32 v117, v120, v120
	v_add_f32_e32 v115, v115, v117
	s_waitcnt vmcnt(3)
	v_pk_add_f32 v[190:191], v[106:107], v[190:191]
	v_pk_add_f32 v[188:189], v[104:105], v[188:189]
	v_cvt_pk_bf16_f32 v105, v190, v191
	v_cvt_pk_bf16_f32 v104, v188, v189
	global_store_dwordx2 v[124:125], v[104:105], off offset:32
	v_mul_f32_e32 v189, v189, v189
	v_mul_f32_e32 v191, v191, v191
	v_fmac_f32_e32 v189, v188, v188
	v_fmac_f32_e32 v191, v190, v190
	v_add_f32_e32 v188, v189, v191
	v_add_f32_e32 v188, v115, v188
	s_waitcnt vmcnt(3)
	v_pk_add_f32 v[194:195], v[102:103], v[194:195]
	v_pk_add_f32 v[192:193], v[100:101], v[192:193]
	v_cvt_pk_bf16_f32 v101, v194, v195
	v_cvt_pk_bf16_f32 v100, v192, v193
	global_store_dwordx2 v[124:125], v[100:101], off offset:256
	v_mul_f32_e32 v193, v193, v193
	v_mul_f32_e32 v195, v195, v195
	v_fmac_f32_e32 v193, v192, v192
	v_fmac_f32_e32 v195, v194, v194
	v_add_f32_e32 v192, v193, v195
	v_add_f32_e32 v192, v188, v192
	s_waitcnt vmcnt(3)
	v_pk_add_f32 v[98:99], v[98:99], v[198:199]
	v_pk_add_f32 v[196:197], v[96:97], v[196:197]
	v_mul_f32_e32 v97, v99, v99
	v_mul_f32_e32 v96, v197, v197
	v_fmac_f32_e32 v96, v196, v196
	v_fmac_f32_e32 v97, v98, v98
	v_add_f32_e32 v96, v96, v97
	v_add_f32_e32 v96, v192, v96
	ds_bpermute_b32 v97, v116, v96
	v_cvt_pk_bf16_f32 v196, v196, v197
	v_cvt_pk_bf16_f32 v197, v98, v99
	global_store_dwordx2 v[124:125], v[196:197], off offset:288
	s_waitcnt lgkmcnt(0)
	v_add_f32_e32 v96, v96, v97
	ds_bpermute_b32 v97, v114, v96
	s_and_saveexec_b64 s[40:41], s[0:1]
	s_cbranch_execz .LBB0_536
	v_lshlrev_b64 v[98:99], 6, v[112:113]
	v_lshl_add_u64 v[98:99], s[18:19], 0, v[98:99]
	v_lshl_add_u64 v[98:99], s[4:5], 2, v[98:99]
	s_lshl_b32 s22, s70, 2
	v_lshl_add_u64 v[98:99], v[98:99], 0, s[22:23]
	s_waitcnt lgkmcnt(0)
	v_add_f32_e32 v96, v96, v97
	global_store_dword v[98:99], v96, off
; __device__ __forceinline__ unsigned pk2(float lo, float hi) { f32x2 v = {lo, hi}; bf16x2_t b = __builtin_convertvector(v, bf16x2_t); return __builtin_bit_cast(unsigned, b); }
; __device__ __forceinline__ float bflo(unsigned u) { return __uint_as_float(u << 16); }
; __device__ __forceinline__ float bfhi(unsigned u) { return __uint_as_float(u & 0xffff0000u); }
;     __device__ __forceinline__ void operator()(const pg8::f32x4 (&acc)[2][2][4][2], const pg8::Unit& u, int wr, int wc, int fr, int fq) const {
;     ...
;         for (int ai = 0; ai < 2; ++ai)
; #pragma unroll
;             for (int m = 0; m < 4; ++m) { const int row = u.pm * 256 + ai * 128 + wr * 64 + m * 16 + fr;
;                 const float* rb = (row < TP ? res0 : res1) + (size_t)row * DM; bf16_t* xr = X + (size_t)row * DM; float ss = 0.f;
; #pragma unroll
;                 for (int bj = 0; bj < 2; ++bj)
; #pragma unroll
;                     for (int n = 0; n < 2; ++n) { const int col = col0 + bj * 128 + n * 16;
;                         f32x4 r;
;                         if (RES_F32) r = *(const f32x4*)(rb + col);
;                         else { const u32x2 rw = *(const u32x2*)(xr + col); r = (f32x4){bflo(rw.x), bfhi(rw.x), bflo(rw.y), bfhi(rw.y)}; }
;                         const f32x4 x = r + acc[ai][bj][m][n];
;                         ss += (x[0] * x[0] + x[1] * x[1]) + (x[2] * x[2] + x[3] * x[3]);
;                         u32x2 o; o.x = pk2(x[0], x[1]); o.y = pk2(x[2], x[3]); *(u32x2*)(xr + col) = o; }
;                 ss += __shfl_xor(ss, 16); ss += __shfl_xor(ss, 32); if (fq == 0) part[(size_t)row * 16 + u.pn * 4 + wc] = ss; }
.LBB0_536:
	s_or_b64 exec, exec, s[40:41]
	v_or_b32_e32 v96, 32, v146
	s_waitcnt lgkmcnt(0)
	v_mov_b32_e32 v97, s69
	v_mov_b32_e32 v98, s9
	v_cmp_gt_i32_e32 vcc, s73, v96
	s_nop 1
	v_cndmask_b32_e32 v99, v97, v98, vcc
	v_mov_b32_e32 v97, s68
	v_mov_b32_e32 v98, s8
	v_cndmask_b32_e32 v98, v97, v98, vcc
	v_ashrrev_i32_e32 v97, 31, v96
	v_lshlrev_b64 v[100:101], 12, v[96:97]
	v_lshl_add_u64 v[98:99], v[98:99], 0, v[100:101]
	v_lshl_add_u64 v[102:103], v[144:145], 2, v[98:99]
	global_load_dwordx4 v[98:101], v[102:103], off
	global_load_dwordx4 v[188:191], v[102:103], off offset:64
	global_load_dwordx4 v[192:195], v[102:103], off offset:512
	global_load_dwordx4 v[196:199], v[102:103], off offset:576
	v_lshlrev_b64 v[104:105], 11, v[96:97]
	v_lshl_add_u64 v[104:105], s[66:67], 0, v[104:105]
	v_lshl_add_u64 v[104:105], v[144:145], 1, v[104:105]
	s_waitcnt vmcnt(3)
	v_pk_add_f32 v[100:101], v[94:95], v[100:101]
	v_pk_add_f32 v[98:99], v[92:93], v[98:99]
	v_cvt_pk_bf16_f32 v93, v100, v101
	v_cvt_pk_bf16_f32 v92, v98, v99
	global_store_dwordx2 v[104:105], v[92:93], off
	v_mul_f32_e32 v99, v99, v99
	v_mul_f32_e32 v101, v101, v101
	v_fmac_f32_e32 v99, v98, v98
	v_fmac_f32_e32 v101, v100, v100
	v_add_f32_e32 v98, v99, v101
	s_waitcnt vmcnt(3)
	v_pk_add_f32 v[190:191], v[90:91], v[190:191]
	v_pk_add_f32 v[188:189], v[88:89], v[188:189]
	v_cvt_pk_bf16_f32 v89, v190, v191
	v_cvt_pk_bf16_f32 v88, v188, v189
	global_store_dwordx2 v[104:105], v[88:89], off offset:32
	v_mul_f32_e32 v189, v189, v189
	v_mul_f32_e32 v191, v191, v191
	v_fmac_f32_e32 v189, v188, v188
	v_fmac_f32_e32 v191, v190, v190
	v_add_f32_e32 v188, v189, v191
	v_add_f32_e32 v188, v98, v188
	s_waitcnt vmcnt(3)
	v_pk_add_f32 v[194:195], v[86:87], v[194:195]
	v_pk_add_f32 v[192:193], v[84:85], v[192:193]
	v_cvt_pk_bf16_f32 v85, v194, v195
	v_cvt_pk_bf16_f32 v84, v192, v193
	global_store_dwordx2 v[104:105], v[84:85], off offset:256
	v_mul_f32_e32 v193, v193, v193
	v_mul_f32_e32 v195, v195, v195
	v_fmac_f32_e32 v193, v192, v192
	v_fmac_f32_e32 v195, v194, v194
	v_add_f32_e32 v192, v193, v195
	v_add_f32_e32 v192, v188, v192
	s_waitcnt vmcnt(3)
	v_pk_add_f32 v[82:83], v[82:83], v[198:199]
	v_pk_add_f32 v[196:197], v[80:81], v[196:197]
	v_mul_f32_e32 v81, v83, v83
	v_mul_f32_e32 v80, v197, v197
	v_fmac_f32_e32 v80, v196, v196
	v_fmac_f32_e32 v81, v82, v82
	v_add_f32_e32 v80, v80, v81
	v_add_f32_e32 v80, v192, v80
	ds_bpermute_b32 v81, v116, v80
	v_cvt_pk_bf16_f32 v196, v196, v197
	v_cvt_pk_bf16_f32 v197, v82, v83
	global_store_dwordx2 v[104:105], v[196:197], off offset:288
	s_waitcnt lgkmcnt(0)
	v_add_f32_e32 v80, v80, v81
	ds_bpermute_b32 v81, v114, v80
	s_and_saveexec_b64 s[40:41], s[0:1]
	s_cbranch_execz .LBB0_538
	v_lshlrev_b64 v[82:83], 6, v[96:97]
	v_lshl_add_u64 v[82:83], s[18:19], 0, v[82:83]
	v_lshl_add_u64 v[82:83], s[4:5], 2, v[82:83]
	s_lshl_b32 s22, s70, 2
	v_lshl_add_u64 v[82:83], v[82:83], 0, s[22:23]
	s_waitcnt lgkmcnt(0)
	v_add_f32_e32 v80, v80, v81
	global_store_dword v[82:83], v80, off
.LBB0_538:
	s_or_b64 exec, exec, s[40:41]
	v_or_b32_e32 v80, 48, v146
	s_waitcnt lgkmcnt(0)
	v_mov_b32_e32 v81, s69
	v_mov_b32_e32 v82, s9
	v_cmp_gt_i32_e32 vcc, s73, v80
	s_nop 1
	v_cndmask_b32_e32 v83, v81, v82, vcc
	v_mov_b32_e32 v81, s68
	v_mov_b32_e32 v82, s8
	v_cndmask_b32_e32 v82, v81, v82, vcc
	v_ashrrev_i32_e32 v81, 31, v80
	v_lshlrev_b64 v[84:85], 12, v[80:81]
	v_lshl_add_u64 v[82:83], v[82:83], 0, v[84:85]
	v_lshl_add_u64 v[86:87], v[144:145], 2, v[82:83]
	global_load_dwordx4 v[82:85], v[86:87], off
	global_load_dwordx4 v[188:191], v[86:87], off offset:64
	global_load_dwordx4 v[192:195], v[86:87], off offset:512
	global_load_dwordx4 v[196:199], v[86:87], off offset:576
	v_lshlrev_b64 v[88:89], 11, v[80:81]
	v_lshl_add_u64 v[88:89], s[66:67], 0, v[88:89]
	v_lshl_add_u64 v[88:89], v[144:145], 1, v[88:89]
	s_waitcnt vmcnt(3)
	v_pk_add_f32 v[84:85], v[78:79], v[84:85]
	v_pk_add_f32 v[82:83], v[76:77], v[82:83]
	v_cvt_pk_bf16_f32 v77, v84, v85
	v_cvt_pk_bf16_f32 v76, v82, v83
	global_store_dwordx2 v[88:89], v[76:77], off
	v_mul_f32_e32 v83, v83, v83
	v_mul_f32_e32 v85, v85, v85
	v_fmac_f32_e32 v83, v82, v82
	v_fmac_f32_e32 v85, v84, v84
	v_add_f32_e32 v82, v83, v85
	s_waitcnt vmcnt(3)
	v_pk_add_f32 v[190:191], v[74:75], v[190:191]
	v_pk_add_f32 v[188:189], v[72:73], v[188:189]
	v_cvt_pk_bf16_f32 v73, v190, v191
	v_cvt_pk_bf16_f32 v72, v188, v189
	global_store_dwordx2 v[88:89], v[72:73], off offset:32
	v_mul_f32_e32 v189, v189, v189
	v_mul_f32_e32 v191, v191, v191
	v_fmac_f32_e32 v189, v188, v188
	v_fmac_f32_e32 v191, v190, v190
	v_add_f32_e32 v188, v189, v191
	v_add_f32_e32 v188, v82, v188
	s_waitcnt vmcnt(3)
	v_pk_add_f32 v[194:195], v[70:71], v[194:195]
	v_pk_add_f32 v[192:193], v[68:69], v[192:193]
	v_cvt_pk_bf16_f32 v69, v194, v195
	v_cvt_pk_bf16_f32 v68, v192, v193
	global_store_dwordx2 v[88:89], v[68:69], off offset:256
	v_mul_f32_e32 v193, v193, v193
	v_mul_f32_e32 v195, v195, v195
	v_fmac_f32_e32 v193, v192, v192
	v_fmac_f32_e32 v195, v194, v194
	v_add_f32_e32 v192, v193, v195
	v_add_f32_e32 v192, v188, v192
	s_waitcnt vmcnt(3)
	v_pk_add_f32 v[66:67], v[66:67], v[198:199]
	v_pk_add_f32 v[196:197], v[64:65], v[196:197]
	v_mul_f32_e32 v65, v67, v67
	v_mul_f32_e32 v64, v197, v197
	v_fmac_f32_e32 v64, v196, v196
	v_fmac_f32_e32 v65, v66, v66
	v_add_f32_e32 v64, v64, v65
	v_add_f32_e32 v64, v192, v64
	ds_bpermute_b32 v65, v116, v64
	v_cvt_pk_bf16_f32 v196, v196, v197
	v_cvt_pk_bf16_f32 v197, v66, v67
	global_store_dwordx2 v[88:89], v[196:197], off offset:288
	s_waitcnt lgkmcnt(0)
	v_add_f32_e32 v64, v64, v65
	ds_bpermute_b32 v65, v114, v64
	s_and_saveexec_b64 s[40:41], s[0:1]
	s_cbranch_execz .LBB0_540
	v_lshlrev_b64 v[66:67], 6, v[80:81]
	v_lshl_add_u64 v[66:67], s[18:19], 0, v[66:67]
	v_lshl_add_u64 v[66:67], s[4:5], 2, v[66:67]
	s_lshl_b32 s22, s70, 2
	v_lshl_add_u64 v[66:67], v[66:67], 0, s[22:23]
	s_waitcnt lgkmcnt(0)
	v_add_f32_e32 v64, v64, v65
	global_store_dword v[66:67], v64, off
; __device__ __forceinline__ unsigned pk2(float lo, float hi) { f32x2 v = {lo, hi}; bf16x2_t b = __builtin_convertvector(v, bf16x2_t); return __builtin_bit_cast(unsigned, b); }
; __device__ __forceinline__ float bflo(unsigned u) { return __uint_as_float(u << 16); }
; __device__ __forceinline__ float bfhi(unsigned u) { return __uint_as_float(u & 0xffff0000u); }
;     __device__ __forceinline__ void operator()(const pg8::f32x4 (&acc)[2][2][4][2], const pg8::Unit& u, int wr, int wc, int fr, int fq) const {
;     ...
;         for (int ai = 0; ai < 2; ++ai)
; #pragma unroll
;             for (int m = 0; m < 4; ++m) { const int row = u.pm * 256 + ai * 128 + wr * 64 + m * 16 + fr;
;                 const float* rb = (row < TP ? res0 : res1) + (size_t)row * DM; bf16_t* xr = X + (size_t)row * DM; float ss = 0.f;
; #pragma unroll
;                 for (int bj = 0; bj < 2; ++bj)
; #pragma unroll
;                     for (int n = 0; n < 2; ++n) { const int col = col0 + bj * 128 + n * 16;
;                         f32x4 r;
;                         if (RES_F32) r = *(const f32x4*)(rb + col);
;                         else { const u32x2 rw = *(const u32x2*)(xr + col); r = (f32x4){bflo(rw.x), bfhi(rw.x), bflo(rw.y), bfhi(rw.y)}; }
;                         const f32x4 x = r + acc[ai][bj][m][n];
;                         ss += (x[0] * x[0] + x[1] * x[1]) + (x[2] * x[2] + x[3] * x[3]);
;                         u32x2 o; o.x = pk2(x[0], x[1]); o.y = pk2(x[2], x[3]); *(u32x2*)(xr + col) = o; }
;                 ss += __shfl_xor(ss, 16); ss += __shfl_xor(ss, 32); if (fq == 0) part[(size_t)row * 16 + u.pn * 4 + wc] = ss; }
.LBB0_540:
	s_or_b64 exec, exec, s[40:41]
	v_add_u32_e32 v64, 0x80, v146
	s_waitcnt lgkmcnt(0)
	v_mov_b32_e32 v65, s69
	v_mov_b32_e32 v66, s9
	v_cmp_gt_i32_e32 vcc, s73, v64
	s_nop 1
	v_cndmask_b32_e32 v67, v65, v66, vcc
	v_mov_b32_e32 v65, s68
	v_mov_b32_e32 v66, s8
	v_cndmask_b32_e32 v66, v65, v66, vcc
	v_ashrrev_i32_e32 v65, 31, v64
	v_lshlrev_b64 v[68:69], 12, v[64:65]
	v_lshl_add_u64 v[66:67], v[66:67], 0, v[68:69]
	v_lshl_add_u64 v[70:71], v[144:145], 2, v[66:67]
	global_load_dwordx4 v[66:69], v[70:71], off
	global_load_dwordx4 v[188:191], v[70:71], off offset:64
	global_load_dwordx4 v[192:195], v[70:71], off offset:512
	global_load_dwordx4 v[196:199], v[70:71], off offset:576
	v_lshlrev_b64 v[72:73], 11, v[64:65]
	v_lshl_add_u64 v[72:73], s[66:67], 0, v[72:73]
	v_lshl_add_u64 v[72:73], v[144:145], 1, v[72:73]
	s_waitcnt vmcnt(3)
	v_pk_add_f32 v[68:69], v[62:63], v[68:69]
	v_pk_add_f32 v[66:67], v[60:61], v[66:67]
	v_cvt_pk_bf16_f32 v61, v68, v69
	v_cvt_pk_bf16_f32 v60, v66, v67
	global_store_dwordx2 v[72:73], v[60:61], off
	v_mul_f32_e32 v67, v67, v67
	v_mul_f32_e32 v69, v69, v69
	v_fmac_f32_e32 v67, v66, v66
	v_fmac_f32_e32 v69, v68, v68
	v_add_f32_e32 v66, v67, v69
	s_waitcnt vmcnt(3)
	v_pk_add_f32 v[190:191], v[58:59], v[190:191]
	v_pk_add_f32 v[188:189], v[56:57], v[188:189]
	v_cvt_pk_bf16_f32 v57, v190, v191
	v_cvt_pk_bf16_f32 v56, v188, v189
	global_store_dwordx2 v[72:73], v[56:57], off offset:32
	v_mul_f32_e32 v189, v189, v189
	v_mul_f32_e32 v191, v191, v191
	v_fmac_f32_e32 v189, v188, v188
	v_fmac_f32_e32 v191, v190, v190
	v_add_f32_e32 v188, v189, v191
	v_add_f32_e32 v188, v66, v188
	s_waitcnt vmcnt(3)
	v_pk_add_f32 v[194:195], v[54:55], v[194:195]
	v_pk_add_f32 v[192:193], v[52:53], v[192:193]
	v_cvt_pk_bf16_f32 v53, v194, v195
	v_cvt_pk_bf16_f32 v52, v192, v193
	global_store_dwordx2 v[72:73], v[52:53], off offset:256
	v_mul_f32_e32 v193, v193, v193
	v_mul_f32_e32 v195, v195, v195
	v_fmac_f32_e32 v193, v192, v192
	v_fmac_f32_e32 v195, v194, v194
	v_add_f32_e32 v192, v193, v195
	v_add_f32_e32 v192, v188, v192
	s_waitcnt vmcnt(3)
	v_pk_add_f32 v[50:51], v[50:51], v[198:199]
	v_pk_add_f32 v[196:197], v[48:49], v[196:197]
	v_mul_f32_e32 v49, v51, v51
	v_mul_f32_e32 v48, v197, v197
	v_fmac_f32_e32 v48, v196, v196
	v_fmac_f32_e32 v49, v50, v50
	v_add_f32_e32 v48, v48, v49
	v_add_f32_e32 v48, v192, v48
	ds_bpermute_b32 v49, v116, v48
	v_cvt_pk_bf16_f32 v196, v196, v197
	v_cvt_pk_bf16_f32 v197, v50, v51
	global_store_dwordx2 v[72:73], v[196:197], off offset:288
	s_waitcnt lgkmcnt(0)
	v_add_f32_e32 v48, v48, v49
	ds_bpermute_b32 v49, v114, v48
	s_and_saveexec_b64 s[40:41], s[0:1]
	s_cbranch_execz .LBB0_542
	v_lshlrev_b64 v[50:51], 6, v[64:65]
	v_lshl_add_u64 v[50:51], s[18:19], 0, v[50:51]
	v_lshl_add_u64 v[50:51], s[4:5], 2, v[50:51]
	s_lshl_b32 s22, s70, 2
	v_lshl_add_u64 v[50:51], v[50:51], 0, s[22:23]
	s_waitcnt lgkmcnt(0)
	v_add_f32_e32 v48, v48, v49
	global_store_dword v[50:51], v48, off
.LBB0_542:
	s_or_b64 exec, exec, s[40:41]
	v_add_u32_e32 v48, 0x90, v146
	s_waitcnt lgkmcnt(0)
	v_mov_b32_e32 v49, s69
	v_mov_b32_e32 v50, s9
	v_cmp_gt_i32_e32 vcc, s73, v48
	s_nop 1
	v_cndmask_b32_e32 v51, v49, v50, vcc
	v_mov_b32_e32 v49, s68
	v_mov_b32_e32 v50, s8
	v_cndmask_b32_e32 v50, v49, v50, vcc
	v_ashrrev_i32_e32 v49, 31, v48
	v_lshlrev_b64 v[52:53], 12, v[48:49]
	v_lshl_add_u64 v[50:51], v[50:51], 0, v[52:53]
	v_lshl_add_u64 v[54:55], v[144:145], 2, v[50:51]
	global_load_dwordx4 v[50:53], v[54:55], off
	global_load_dwordx4 v[188:191], v[54:55], off offset:64
	global_load_dwordx4 v[192:195], v[54:55], off offset:512
	global_load_dwordx4 v[196:199], v[54:55], off offset:576
	v_lshlrev_b64 v[56:57], 11, v[48:49]
	v_lshl_add_u64 v[56:57], s[66:67], 0, v[56:57]
	v_lshl_add_u64 v[56:57], v[144:145], 1, v[56:57]
	s_waitcnt vmcnt(3)
	v_pk_add_f32 v[52:53], v[46:47], v[52:53]
	v_pk_add_f32 v[50:51], v[44:45], v[50:51]
	v_cvt_pk_bf16_f32 v45, v52, v53
	v_cvt_pk_bf16_f32 v44, v50, v51
	global_store_dwordx2 v[56:57], v[44:45], off
	v_mul_f32_e32 v51, v51, v51
	v_mul_f32_e32 v53, v53, v53
	v_fmac_f32_e32 v51, v50, v50
	v_fmac_f32_e32 v53, v52, v52
	v_add_f32_e32 v50, v51, v53
	s_waitcnt vmcnt(3)
	v_pk_add_f32 v[190:191], v[42:43], v[190:191]
	v_pk_add_f32 v[188:189], v[40:41], v[188:189]
	v_cvt_pk_bf16_f32 v41, v190, v191
	v_cvt_pk_bf16_f32 v40, v188, v189
	global_store_dwordx2 v[56:57], v[40:41], off offset:32
	v_mul_f32_e32 v189, v189, v189
	v_mul_f32_e32 v191, v191, v191
	v_fmac_f32_e32 v189, v188, v188
	v_fmac_f32_e32 v191, v190, v190
	v_add_f32_e32 v188, v189, v191
	v_add_f32_e32 v188, v50, v188
	s_waitcnt vmcnt(3)
	v_pk_add_f32 v[194:195], v[38:39], v[194:195]
	v_pk_add_f32 v[192:193], v[36:37], v[192:193]
	v_cvt_pk_bf16_f32 v37, v194, v195
	v_cvt_pk_bf16_f32 v36, v192, v193
	global_store_dwordx2 v[56:57], v[36:37], off offset:256
	v_mul_f32_e32 v193, v193, v193
	v_mul_f32_e32 v195, v195, v195
	v_fmac_f32_e32 v193, v192, v192
	v_fmac_f32_e32 v195, v194, v194
	v_add_f32_e32 v192, v193, v195
	v_add_f32_e32 v192, v188, v192
	s_waitcnt vmcnt(3)
	v_pk_add_f32 v[34:35], v[34:35], v[198:199]
	v_pk_add_f32 v[196:197], v[32:33], v[196:197]
	v_mul_f32_e32 v33, v35, v35
	v_mul_f32_e32 v32, v197, v197
	v_fmac_f32_e32 v32, v196, v196
	v_fmac_f32_e32 v33, v34, v34
	v_add_f32_e32 v32, v32, v33
	v_add_f32_e32 v32, v192, v32
	ds_bpermute_b32 v33, v116, v32
	v_cvt_pk_bf16_f32 v196, v196, v197
	v_cvt_pk_bf16_f32 v197, v34, v35
	global_store_dwordx2 v[56:57], v[196:197], off offset:288
	s_waitcnt lgkmcnt(0)
	v_add_f32_e32 v32, v32, v33
	ds_bpermute_b32 v33, v114, v32
	s_and_saveexec_b64 s[40:41], s[0:1]
	s_cbranch_execz .LBB0_544
	v_lshlrev_b64 v[34:35], 6, v[48:49]
	v_lshl_add_u64 v[34:35], s[18:19], 0, v[34:35]
	v_lshl_add_u64 v[34:35], s[4:5], 2, v[34:35]
	s_lshl_b32 s22, s70, 2
	v_lshl_add_u64 v[34:35], v[34:35], 0, s[22:23]
	s_waitcnt lgkmcnt(0)
	v_add_f32_e32 v32, v32, v33
	global_store_dword v[34:35], v32, off
; __device__ __forceinline__ unsigned pk2(float lo, float hi) { f32x2 v = {lo, hi}; bf16x2_t b = __builtin_convertvector(v, bf16x2_t); return __builtin_bit_cast(unsigned, b); }
; __device__ __forceinline__ float bflo(unsigned u) { return __uint_as_float(u << 16); }
; __device__ __forceinline__ float bfhi(unsigned u) { return __uint_as_float(u & 0xffff0000u); }
;     __device__ __forceinline__ void operator()(const pg8::f32x4 (&acc)[2][2][4][2], const pg8::Unit& u, int wr, int wc, int fr, int fq) const {
;     ...
;         for (int ai = 0; ai < 2; ++ai)
; #pragma unroll
;             for (int m = 0; m < 4; ++m) { const int row = u.pm * 256 + ai * 128 + wr * 64 + m * 16 + fr;
;                 const float* rb = (row < TP ? res0 : res1) + (size_t)row * DM; bf16_t* xr = X + (size_t)row * DM; float ss = 0.f;
; #pragma unroll
;                 for (int bj = 0; bj < 2; ++bj)
; #pragma unroll
;                     for (int n = 0; n < 2; ++n) { const int col = col0 + bj * 128 + n * 16;
;                         f32x4 r;
;                         if (RES_F32) r = *(const f32x4*)(rb + col);
;                         else { const u32x2 rw = *(const u32x2*)(xr + col); r = (f32x4){bflo(rw.x), bfhi(rw.x), bflo(rw.y), bfhi(rw.y)}; }
;                         const f32x4 x = r + acc[ai][bj][m][n];
;                         ss += (x[0] * x[0] + x[1] * x[1]) + (x[2] * x[2] + x[3] * x[3]);
;                         u32x2 o; o.x = pk2(x[0], x[1]); o.y = pk2(x[2], x[3]); *(u32x2*)(xr + col) = o; }
;                 ss += __shfl_xor(ss, 16); ss += __shfl_xor(ss, 32); if (fq == 0) part[(size_t)row * 16 + u.pn * 4 + wc] = ss; }
.LBB0_544:
	s_or_b64 exec, exec, s[40:41]
	v_add_u32_e32 v32, 0xa0, v146
	s_waitcnt lgkmcnt(0)
	v_mov_b32_e32 v33, s69
	v_mov_b32_e32 v34, s9
	v_cmp_gt_i32_e32 vcc, s73, v32
	s_nop 1
	v_cndmask_b32_e32 v35, v33, v34, vcc
	v_mov_b32_e32 v33, s68
	v_mov_b32_e32 v34, s8
	v_cndmask_b32_e32 v34, v33, v34, vcc
	v_ashrrev_i32_e32 v33, 31, v32
	v_lshlrev_b64 v[36:37], 12, v[32:33]
	v_lshl_add_u64 v[34:35], v[34:35], 0, v[36:37]
	v_lshl_add_u64 v[38:39], v[144:145], 2, v[34:35]
	global_load_dwordx4 v[34:37], v[38:39], off
	global_load_dwordx4 v[188:191], v[38:39], off offset:64
	global_load_dwordx4 v[192:195], v[38:39], off offset:512
	global_load_dwordx4 v[196:199], v[38:39], off offset:576
	v_lshlrev_b64 v[40:41], 11, v[32:33]
	v_lshl_add_u64 v[40:41], s[66:67], 0, v[40:41]
	v_lshl_add_u64 v[40:41], v[144:145], 1, v[40:41]
	s_waitcnt vmcnt(3)
	v_pk_add_f32 v[36:37], v[30:31], v[36:37]
	v_pk_add_f32 v[34:35], v[28:29], v[34:35]
	v_cvt_pk_bf16_f32 v29, v36, v37
	v_cvt_pk_bf16_f32 v28, v34, v35
	global_store_dwordx2 v[40:41], v[28:29], off
	v_mul_f32_e32 v35, v35, v35
	v_mul_f32_e32 v37, v37, v37
	v_fmac_f32_e32 v35, v34, v34
	v_fmac_f32_e32 v37, v36, v36
	v_add_f32_e32 v34, v35, v37
	s_waitcnt vmcnt(3)
	v_pk_add_f32 v[190:191], v[26:27], v[190:191]
	v_pk_add_f32 v[188:189], v[24:25], v[188:189]
	v_cvt_pk_bf16_f32 v25, v190, v191
	v_cvt_pk_bf16_f32 v24, v188, v189
	global_store_dwordx2 v[40:41], v[24:25], off offset:32
	v_mul_f32_e32 v189, v189, v189
	v_mul_f32_e32 v191, v191, v191
	v_fmac_f32_e32 v189, v188, v188
	v_fmac_f32_e32 v191, v190, v190
	v_add_f32_e32 v188, v189, v191
	v_add_f32_e32 v188, v34, v188
	s_waitcnt vmcnt(3)
	v_pk_add_f32 v[194:195], v[22:23], v[194:195]
	v_pk_add_f32 v[192:193], v[20:21], v[192:193]
	v_cvt_pk_bf16_f32 v21, v194, v195
	v_cvt_pk_bf16_f32 v20, v192, v193
	global_store_dwordx2 v[40:41], v[20:21], off offset:256
	v_mul_f32_e32 v193, v193, v193
	v_mul_f32_e32 v195, v195, v195
	v_fmac_f32_e32 v193, v192, v192
	v_fmac_f32_e32 v195, v194, v194
	v_add_f32_e32 v192, v193, v195
	v_add_f32_e32 v192, v188, v192
	s_waitcnt vmcnt(3)
	v_pk_add_f32 v[18:19], v[18:19], v[198:199]
	v_pk_add_f32 v[196:197], v[16:17], v[196:197]
	v_mul_f32_e32 v17, v19, v19
	v_mul_f32_e32 v16, v197, v197
	v_fmac_f32_e32 v16, v196, v196
	v_fmac_f32_e32 v17, v18, v18
	v_add_f32_e32 v16, v16, v17
	v_add_f32_e32 v16, v192, v16
	ds_bpermute_b32 v17, v116, v16
	v_cvt_pk_bf16_f32 v196, v196, v197
	v_cvt_pk_bf16_f32 v197, v18, v19
	global_store_dwordx2 v[40:41], v[196:197], off offset:288
	s_waitcnt lgkmcnt(0)
	v_add_f32_e32 v16, v16, v17
	ds_bpermute_b32 v17, v114, v16
	s_and_saveexec_b64 s[40:41], s[0:1]
	s_cbranch_execz .LBB0_546
	v_lshlrev_b64 v[18:19], 6, v[32:33]
	v_lshl_add_u64 v[18:19], s[18:19], 0, v[18:19]
	v_lshl_add_u64 v[18:19], s[4:5], 2, v[18:19]
	s_lshl_b32 s22, s70, 2
	v_lshl_add_u64 v[18:19], v[18:19], 0, s[22:23]
	s_waitcnt lgkmcnt(0)
	v_add_f32_e32 v16, v16, v17
	global_store_dword v[18:19], v16, off
.LBB0_546:
	s_or_b64 exec, exec, s[40:41]
	v_add_u32_e32 v16, 0xb0, v146
	s_waitcnt lgkmcnt(0)
	v_mov_b32_e32 v17, s69
	v_mov_b32_e32 v18, s9
	v_cmp_gt_i32_e32 vcc, s73, v16
	s_nop 1
	v_cndmask_b32_e32 v19, v17, v18, vcc
	v_mov_b32_e32 v17, s68
	v_mov_b32_e32 v18, s8
	v_cndmask_b32_e32 v18, v17, v18, vcc
	v_ashrrev_i32_e32 v17, 31, v16
	v_lshlrev_b64 v[20:21], 12, v[16:17]
	v_lshl_add_u64 v[18:19], v[18:19], 0, v[20:21]
	v_lshl_add_u64 v[22:23], v[144:145], 2, v[18:19]
	global_load_dwordx4 v[18:21], v[22:23], off
	global_load_dwordx4 v[188:191], v[22:23], off offset:64
	global_load_dwordx4 v[192:195], v[22:23], off offset:512
	global_load_dwordx4 v[196:199], v[22:23], off offset:576
	v_lshlrev_b64 v[24:25], 11, v[16:17]
	v_lshl_add_u64 v[24:25], s[66:67], 0, v[24:25]
	v_lshl_add_u64 v[24:25], v[144:145], 1, v[24:25]
	s_waitcnt vmcnt(3)
	v_pk_add_f32 v[20:21], v[14:15], v[20:21]
	v_pk_add_f32 v[18:19], v[12:13], v[18:19]
	v_cvt_pk_bf16_f32 v13, v20, v21
	v_cvt_pk_bf16_f32 v12, v18, v19
	global_store_dwordx2 v[24:25], v[12:13], off
	v_mul_f32_e32 v19, v19, v19
	v_mul_f32_e32 v21, v21, v21
	v_fmac_f32_e32 v19, v18, v18
	v_fmac_f32_e32 v21, v20, v20
	v_add_f32_e32 v18, v19, v21
	s_waitcnt vmcnt(3)
	v_pk_add_f32 v[190:191], v[10:11], v[190:191]
	v_pk_add_f32 v[188:189], v[8:9], v[188:189]
	v_cvt_pk_bf16_f32 v9, v190, v191
	v_cvt_pk_bf16_f32 v8, v188, v189
	global_store_dwordx2 v[24:25], v[8:9], off offset:32
	v_mul_f32_e32 v189, v189, v189
	v_mul_f32_e32 v191, v191, v191
	v_fmac_f32_e32 v189, v188, v188
	v_fmac_f32_e32 v191, v190, v190
	v_add_f32_e32 v188, v189, v191
	v_add_f32_e32 v188, v18, v188
	s_waitcnt vmcnt(3)
	v_pk_add_f32 v[194:195], v[6:7], v[194:195]
	v_pk_add_f32 v[192:193], v[4:5], v[192:193]
	v_cvt_pk_bf16_f32 v5, v194, v195
	v_cvt_pk_bf16_f32 v4, v192, v193
	global_store_dwordx2 v[24:25], v[4:5], off offset:256
	v_mul_f32_e32 v193, v193, v193
	v_mul_f32_e32 v195, v195, v195
	v_fmac_f32_e32 v193, v192, v192
	v_fmac_f32_e32 v195, v194, v194
	v_add_f32_e32 v192, v193, v195
	v_add_f32_e32 v192, v188, v192
	s_waitcnt vmcnt(3)
	v_pk_add_f32 v[2:3], v[2:3], v[198:199]
	v_pk_add_f32 v[196:197], v[0:1], v[196:197]
	v_mul_f32_e32 v1, v3, v3
	v_mul_f32_e32 v0, v197, v197
	v_fmac_f32_e32 v0, v196, v196
	v_fmac_f32_e32 v1, v2, v2
	v_add_f32_e32 v0, v0, v1
	v_add_f32_e32 v0, v192, v0
	ds_bpermute_b32 v1, v116, v0
	v_cvt_pk_bf16_f32 v196, v196, v197
	v_cvt_pk_bf16_f32 v197, v2, v3
	global_store_dwordx2 v[24:25], v[196:197], off offset:288
	s_waitcnt lgkmcnt(0)
	v_add_f32_e32 v0, v0, v1
	ds_bpermute_b32 v1, v114, v0
	s_and_saveexec_b64 s[40:41], s[0:1]
	s_cbranch_execz .LBB0_548
	v_lshlrev_b64 v[2:3], 6, v[16:17]
	v_lshl_add_u64 v[2:3], s[18:19], 0, v[2:3]
	v_lshl_add_u64 v[2:3], s[4:5], 2, v[2:3]
	s_lshl_b32 s22, s70, 2
	v_lshl_add_u64 v[2:3], v[2:3], 0, s[22:23]
	s_waitcnt lgkmcnt(0)
	v_add_f32_e32 v0, v0, v1
	global_store_dword v[2:3], v0, off

; __device__ __forceinline__ float bflo(unsigned u) { return __uint_as_float(u << 16); }
; __device__ __forceinline__ float bfhi(unsigned u) { return __uint_as_float(u & 0xffff0000u); }
; __device__ __forceinline__ void attn_unit(LAS unsigned char* L, bf16_t* QKV, size_t rowbase, int S, int h, int qb, float lam, const float* subln, unsigned* kmax) {
;     ...
;         const int seq = rowbase < (size_t)TP ? (int)(rowbase >> 14) : 2 + (int)((rowbase - TP) >> 13);
;         unsigned* kp = kmax + (seq * 16 + 2 * h + hd) * 2;
;         const float kb = sqrtf(__uint_as_float(__hip_atomic_load(kp, __ATOMIC_RELAXED, __HIP_MEMORY_SCOPE_AGENT)) + __uint_as_float(__hip_atomic_load(kp + 1, __ATOMIC_RELAXED, __HIP_MEMORY_SCOPE_AGENT)));
;         float q2 = 0.f;
; #pragma unroll
;         for (int st = 0; st < 4; ++st) { const u32x4 w = __builtin_bit_cast(u32x4, qf[st]);
;             q2 += ((bflo(w.x) * bflo(w.x) + bfhi(w.x) * bfhi(w.x)) + (bflo(w.y) * bflo(w.y) + bfhi(w.y) * bfhi(w.y))) + ((bflo(w.z) * bflo(w.z) + bfhi(w.z) * bfhi(w.z)) + (bflo(w.w) * bflo(w.w) + bfhi(w.w) * bfhi(w.w))); }
;         q2 += __shfl_xor(q2, 32);
.LBB0_926:
	s_lshl_b32 s5, s63, 2
	s_lshl_b32 s10, s40, 1
	s_lshl_b32 s4, s22, 5
	s_add_i32 s5, s10, s5
	s_add_i32 s10, s5, s4
	s_lshl_b32 s23, s40, 3
	s_lshl_b64 s[4:5], s[10:11], 2
	s_add_u32 s4, s26, s4
	s_addc_u32 s5, s27, s5
	global_load_dword v25, v157, s[4:5] sc1
	global_load_dword v27, v157, s[4:5] offset:4 sc1
	s_waitcnt vmcnt(5)
	v_and_b32_e32 v3, 0xffff0000, v113
	v_and_b32_e32 v2, 0xffff0000, v112
	v_and_b32_e32 v7, 0xffff0000, v115
	v_and_b32_e32 v6, 0xffff0000, v114
	s_waitcnt vmcnt(4)
	v_and_b32_e32 v11, 0xffff0000, v117
	v_and_b32_e32 v10, 0xffff0000, v116
	v_and_b32_e32 v15, 0xffff0000, v119
	v_and_b32_e32 v14, 0xffff0000, v118
	v_lshlrev_b32_e32 v1, 16, v113
	v_lshlrev_b32_e32 v0, 16, v112
	v_lshlrev_b32_e32 v5, 16, v115
	v_lshlrev_b32_e32 v4, 16, v114
	v_lshlrev_b32_e32 v9, 16, v117
	v_lshlrev_b32_e32 v8, 16, v116
	v_lshlrev_b32_e32 v13, 16, v119
	v_lshlrev_b32_e32 v12, 16, v118
	v_pk_mul_f32 v[2:3], v[2:3], v[2:3]
	v_pk_mul_f32 v[6:7], v[6:7], v[6:7]
	v_pk_mul_f32 v[10:11], v[10:11], v[10:11]
	v_pk_mul_f32 v[14:15], v[14:15], v[14:15]
	s_waitcnt vmcnt(2)
	v_lshlrev_b32_e32 v24, 16, v124
	v_and_b32_e32 v26, 0xffff0000, v124
	v_lshlrev_b32_e32 v28, 16, v125
	v_and_b32_e32 v29, 0xffff0000, v125
	v_pk_fma_f32 v[0:1], v[0:1], v[0:1], v[2:3]
	v_pk_fma_f32 v[2:3], v[4:5], v[4:5], v[6:7]
	v_pk_fma_f32 v[4:5], v[8:9], v[8:9], v[10:11]
	v_pk_fma_f32 v[6:7], v[12:13], v[12:13], v[14:15]
	v_mul_f32_e32 v35, v24, v24
	v_mul_f32_e32 v36, v26, v26
	v_mul_f32_e32 v37, v28, v28
	v_mul_f32_e32 v29, v29, v29
	v_pk_add_f32 v[0:1], v[0:1], v[0:1] op_sel:[0,1] op_sel_hi:[1,0]
	v_pk_add_f32 v[2:3], v[2:3], v[2:3] op_sel:[0,1] op_sel_hi:[1,0]
	v_pk_add_f32 v[4:5], v[4:5], v[4:5] op_sel:[0,1] op_sel_hi:[1,0]
	v_pk_add_f32 v[6:7], v[6:7], v[6:7] op_sel:[0,1] op_sel_hi:[1,0]
	v_mov_b32_e32 v1, v35
	v_mov_b32_e32 v3, v36
	v_mov_b32_e32 v5, v37
	v_mov_b32_e32 v7, v29
	v_pk_add_f32 v[0:1], v[0:1], v[2:3]
	v_pk_add_f32 v[2:3], v[4:5], v[6:7]
	v_and_b32_e32 v17, 0xffff0000, v120
	v_and_b32_e32 v19, 0xffff0000, v121
	v_and_b32_e32 v21, 0xffff0000, v122
	v_and_b32_e32 v23, 0xffff0000, v123
	v_lshlrev_b32_e32 v30, 16, v126
	v_and_b32_e32 v31, 0xffff0000, v126
	v_pk_add_f32 v[0:1], v[0:1], v[2:3]
	v_lshlrev_b32_e32 v16, 16, v120
	v_lshlrev_b32_e32 v18, 16, v121
	v_lshlrev_b32_e32 v20, 16, v122
	v_lshlrev_b32_e32 v22, 16, v123
	v_lshlrev_b32_e32 v32, 16, v127
	v_and_b32_e32 v33, 0xffff0000, v127
	v_mul_f32_e32 v38, v30, v30
	v_mul_f32_e32 v31, v31, v31
	v_mul_f32_e32 v24, v17, v17
	v_mul_f32_e32 v26, v19, v19
	v_mul_f32_e32 v28, v21, v21
	v_mul_f32_e32 v30, v23, v23
	v_mul_f32_e32 v32, v32, v32
	v_mul_f32_e32 v33, v33, v33
	v_pk_fma_f32 v[12:13], v[20:21], v[20:21], v[28:29] op_sel_hi:[1,1,0]
	v_pk_fma_f32 v[14:15], v[22:23], v[22:23], v[30:31] op_sel_hi:[1,1,0]
	v_mov_b32_e32 v13, v32
	v_mov_b32_e32 v15, v33
	v_and_b32_e32 v6, 64, v186
	v_add_u32_e32 v6, 64, v6
	v_bitop3_b32 v34, s23, v171, v181 bitop3:0x36
	v_lshl_add_u32 v34, v34, 4, v172
	v_add_u32_e32 v188, 0, v34
	s_waitcnt vmcnt(0)
	s_barrier
; __device__ __forceinline__ float bflo(unsigned u) { return __uint_as_float(u << 16); }
; __device__ __forceinline__ float bfhi(unsigned u) { return __uint_as_float(u & 0xffff0000u); }
; #define DMA_WAIT_BAR() do { asm volatile("s_waitcnt vmcnt(0)" ::: "memory"); __syncthreads(); } while (0)
; #define RD_K(slot) do { const LAS unsigned char* kp_ = L + (slot) * ASLOT; \
;         _Pragma("unroll") for (int st = 0; st < 4; ++st) { kf[2 * st] = *(const LAS bf16x8*)(kp_ + (kb0 ^ (32 * st))); kf[2 * st + 1] = *(const LAS bf16x8*)(kp_ + 8192 + (kb0 ^ (32 * st))); } } while (0)
; __device__ __forceinline__ void attn_unit(LAS unsigned char* L, bf16_t* QKV, size_t rowbase, int S, int h, int qb, float lam, const float* subln, unsigned* kmax) {
;     ...
;         const int seq = rowbase < (size_t)TP ? (int)(rowbase >> 14) : 2 + (int)((rowbase - TP) >> 13);
;         unsigned* kp = kmax + (seq * 16 + 2 * h + hd) * 2;
;         const float kb = sqrtf(__uint_as_float(__hip_atomic_load(kp, __ATOMIC_RELAXED, __HIP_MEMORY_SCOPE_AGENT)) + __uint_as_float(__hip_atomic_load(kp + 1, __ATOMIC_RELAXED, __HIP_MEMORY_SCOPE_AGENT)));
;         float q2 = 0.f;
; #pragma unroll
;         for (int st = 0; st < 4; ++st) { const u32x4 w = __builtin_bit_cast(u32x4, qf[st]);
;             q2 += ((bflo(w.x) * bflo(w.x) + bfhi(w.x) * bfhi(w.x)) + (bflo(w.y) * bflo(w.y) + bfhi(w.y) * bfhi(w.y))) + ((bflo(w.z) * bflo(w.z) + bfhi(w.z) * bfhi(w.z)) + (bflo(w.w) * bflo(w.w) + bfhi(w.w) * bfhi(w.w))); }
;         q2 += __shfl_xor(q2, 32);
;         const float mref = sqrtf(q2) * kb;
; #pragma unroll
;         for (int r = 0; r < 16; ++r) negm[r] = -mref; }
;     DMA_WAIT_BAR();
;     bf16x8 kf[8], va[4], vb[4];
;     ...
;     RD_K(0);
	ds_read_b128 v[80:83], v188
	ds_read_b128 v[128:131], v188 offset:8192
	v_mov_b32_e32 v187, 0
	s_waitcnt vmcnt(1)
	v_pk_fma_f32 v[8:9], v[16:17], v[16:17], v[24:25] op_sel_hi:[1,1,0]
	s_waitcnt vmcnt(0)
	v_add_f32_e32 v2, v27, v25
	v_mul_f32_e32 v3, 0x4f800000, v2
	v_cmp_gt_f32_e32 vcc, s37, v2
	v_pk_fma_f32 v[10:11], v[18:19], v[18:19], v[26:27] op_sel_hi:[1,1,0]
	v_mov_b32_e32 v9, v38
	v_cndmask_b32_e32 v4, v2, v3, vcc
	v_mov_b32_e32 v11, v31
	v_sqrt_f32_e32 v5, v4
	v_pk_add_f32 v[8:9], v[8:9], v[10:11]
	v_pk_add_f32 v[10:11], v[12:13], v[14:15]
	s_add_i32 s24, s42, -1
	v_pk_add_f32 v[2:3], v[8:9], v[10:11]
	s_add_i32 s25, s43, 0x1c000
	v_pk_add_f32 v[0:1], v[0:1], v[2:3]
	v_xor_b32_e32 v3, 32, v186
	v_add_f32_e32 v0, v0, v1
	v_add_u32_e32 v1, -1, v5
	v_fma_f32 v2, -v1, v5, v4
	v_cmp_ge_f32_e64 s[4:5], 0, v2
	v_add_u32_e32 v2, 1, v5
	s_add_i32 s63, s43, 0x1e000
	v_cndmask_b32_e64 v1, v5, v1, s[4:5]
	v_cmp_lt_i32_e64 s[4:5], v3, v6
	v_fma_f32 v5, -v2, v5, v4
	s_mov_b32 s68, 7
	v_cndmask_b32_e64 v3, v186, v3, s[4:5]
	v_lshlrev_b32_e32 v156, 2, v3
	ds_bpermute_b32 v3, v156, v0
	v_cmp_lt_f32_e64 s[4:5], 0, v5
	v_mov_b32_e32 v192, 0
	v_mov_b32_e32 v193, 0
	v_cndmask_b32_e64 v1, v1, v2, s[4:5]
	s_waitcnt lgkmcnt(0)
	v_add_f32_e32 v0, v0, v3
	v_mul_f32_e32 v3, 0x4f800000, v0
	v_cmp_gt_f32_e64 s[4:5], s37, v0
	v_mul_f32_e32 v2, 0x37800000, v1
	v_cndmask_b32_e32 v1, v1, v2, vcc
	v_cndmask_b32_e64 v0, v0, v3, s[4:5]
	v_sqrt_f32_e32 v3, v0
	v_cmp_class_f32_e32 vcc, v4, v173
	v_mov_b32_e32 v194, 0
	v_mov_b32_e32 v5, v187
	v_add_u32_e32 v2, -1, v3
	v_cndmask_b32_e32 v1, v1, v4, vcc
	v_fma_f32 v4, -v2, v3, v0
	v_cmp_ge_f32_e32 vcc, 0, v4
	v_add_u32_e32 v4, 1, v3
	v_mov_b32_e32 v6, v187
	v_cndmask_b32_e32 v2, v3, v2, vcc
	v_fma_f32 v3, -v4, v3, v0
	v_cmp_lt_f32_e32 vcc, 0, v3
	v_mov_b32_e32 v7, v187
	v_mov_b32_e32 v8, v187
	v_cndmask_b32_e32 v2, v2, v4, vcc
	v_mul_f32_e32 v3, 0x37800000, v2
	v_cndmask_b32_e64 v2, v2, v3, s[4:5]
	v_cmp_class_f32_e32 vcc, v0, v173
	v_mov_b32_e32 v3, v187
	v_mov_b32_e32 v4, v187
	v_cndmask_b32_e32 v0, v2, v0, vcc
	v_mul_f32_e64 v64, v0, -v1
	v_xor_b32_e32 v0, 32, v34
	v_add_u32_e32 v189, 0, v0
	v_xor_b32_e32 v0, 64, v34
	v_add_u32_e32 v190, 0, v0
	v_xor_b32_e32 v0, 0x60, v34
	v_add_u32_e32 v191, 0, v0
	ds_read_b128 v[132:135], v189
	ds_read_b128 v[136:139], v189 offset:8192
	ds_read_b128 v[140:143], v190
	ds_read_b128 v[144:147], v190 offset:8192
	ds_read_b128 v[148:151], v191
	ds_read_b128 v[152:155], v191 offset:8192
	v_mov_b32_e32 v65, v64
	v_mov_b32_e32 v66, v64
	v_mov_b32_e32 v67, v64
	v_mov_b32_e32 v68, v64
	v_mov_b32_e32 v69, v64
	v_mov_b32_e32 v70, v64
	v_mov_b32_e32 v71, v64
	v_mov_b32_e32 v72, v64
	v_mov_b32_e32 v73, v64
	v_mov_b32_e32 v74, v64
	v_mov_b32_e32 v75, v64
	v_mov_b32_e32 v76, v64
	v_mov_b32_e32 v77, v64
	v_mov_b32_e32 v78, v64
	v_mov_b32_e32 v79, v64
	v_mov_b32_e32 v0, 0
	v_mov_b32_e32 v1, v187
	v_mov_b32_e32 v2, v187
	v_mov_b32_e32 v9, v187
	v_mov_b32_e32 v10, v187
	v_mov_b32_e32 v11, v187
	v_mov_b32_e32 v12, v187
	v_mov_b32_e32 v13, v187
	v_mov_b32_e32 v14, v187
	v_mov_b32_e32 v15, v187
	v_mov_b32_e32 v16, 0
	v_mov_b32_e32 v17, v187
	v_mov_b32_e32 v18, v187
	v_mov_b32_e32 v19, v187
	v_mov_b32_e32 v20, v187
	v_mov_b32_e32 v21, v187
	v_mov_b32_e32 v22, v187
	v_mov_b32_e32 v23, v187
	v_mov_b32_e32 v24, v187
	v_mov_b32_e32 v25, v187
	v_mov_b32_e32 v26, v187
	v_mov_b32_e32 v27, v187
	v_mov_b32_e32 v28, v187
	v_mov_b32_e32 v29, v187
	v_mov_b32_e32 v30, v187
	v_mov_b32_e32 v31, v187
	v_mov_b32_e32 v32, 0
	v_mov_b32_e32 v33, v187
	v_mov_b32_e32 v34, v187
	v_mov_b32_e32 v35, v187
	v_mov_b32_e32 v36, v187
	v_mov_b32_e32 v37, v187
	v_mov_b32_e32 v38, v187
	v_mov_b32_e32 v39, v187
	v_mov_b32_e32 v40, v187
	v_mov_b32_e32 v41, v187
	v_mov_b32_e32 v42, v187
	v_mov_b32_e32 v43, v187
	v_mov_b32_e32 v44, v187
	v_mov_b32_e32 v45, v187
	v_mov_b32_e32 v46, v187
	v_mov_b32_e32 v47, v187
	v_mov_b32_e32 v48, 0
	v_mov_b32_e32 v49, v187
	v_mov_b32_e32 v50, v187
	v_mov_b32_e32 v51, v187
	v_mov_b32_e32 v52, v187
	v_mov_b32_e32 v53, v187
	v_mov_b32_e32 v54, v187
	v_mov_b32_e32 v55, v187
	v_mov_b32_e32 v56, v187
	v_mov_b32_e32 v57, v187
	v_mov_b32_e32 v58, v187
	v_mov_b32_e32 v59, v187
	v_mov_b32_e32 v60, v187
	v_mov_b32_e32 v61, v187
	v_mov_b32_e32 v62, v187
	v_mov_b32_e32 v63, v187
	s_add_u32 s22, s20, 0x10000
	s_addc_u32 s23, s21, 0
	v_add_u32_e32 v254, 0x4000, v163
	v_add_u32_e32 v255, 0x100, v163
	v_add_u32_e32 v253, 0x4100, v163
	s_cmp_eq_u32 s40, 1
	s_cbranch_scc0 .Lattn_noprio
	s_setprio 1

.LBB0_927:
	s_add_i32 s69, s68, -3
	s_add_i32 s10, s68, -4
	s_min_u32 s10, s10, s24
	s_lshl_b32 s10, s10, 15
	s_add_u32 s4, s20, s10
	s_addc_u32 s5, s21, 0
	ds_read_b64_tr_b16 v[224:225], v174
	ds_read_b64_tr_b16 v[226:227], v175 offset:2048
	ds_read_b64_tr_b16 v[228:229], v176
	ds_read_b64_tr_b16 v[230:231], v177 offset:2048
	ds_read_b64_tr_b16 v[232:233], v178
	ds_read_b64_tr_b16 v[234:235], v179 offset:2048
	ds_read_b64_tr_b16 v[236:237], v183
	ds_read_b64_tr_b16 v[238:239], v184 offset:2048
	s_mov_b32 m0, s53
	v_mfma_f32_32x32x16_bf16 v[96:111], v[80:83], v[112:115], v[64:79]
	global_load_lds_dwordx4 v163, s[4:5]
	s_mov_b32 m0, s58
	v_mfma_f32_32x32x16_bf16 v[96:111], v[132:135], v[116:119], v[96:111]
	global_load_lds_dwordx4 v254, s[4:5]
	s_mov_b32 m0, s59
	v_mfma_f32_32x32x16_bf16 v[96:111], v[140:143], v[120:123], v[96:111]
	global_load_lds_dwordx4 v255, s[22:23]
	ds_read_b64_tr_b16 v[132:133], v176 offset:4096
	ds_read_b64_tr_b16 v[134:135], v177 offset:6144
	s_mov_b32 m0, s61
	v_mfma_f32_32x32x16_bf16 v[96:111], v[148:151], v[124:127], v[96:111]
	global_load_lds_dwordx4 v253, s[22:23]
	ds_read_b64_tr_b16 v[140:141], v183 offset:4096
	ds_read_b64_tr_b16 v[142:143], v184 offset:6144
	v_mfma_f32_32x32x16_bf16 v[80:95], v[128:131], v[112:115], v[64:79]
	ds_read_b64_tr_b16 v[128:129], v174 offset:4096
	ds_read_b64_tr_b16 v[130:131], v175 offset:6144
	v_mfma_f32_32x32x16_bf16 v[80:95], v[136:139], v[116:119], v[80:95]
	s_nop 3
	v_mfma_f32_32x32x16_bf16 v[80:95], v[144:147], v[120:123], v[80:95]
	v_exp_f32_e32 v96, v96
	v_exp_f32_e32 v97, v97
	v_exp_f32_e32 v98, v98
	v_mfma_f32_32x32x16_bf16 v[80:95], v[152:155], v[124:127], v[80:95]
	v_exp_f32_e32 v99, v99
	v_exp_f32_e32 v100, v100
	v_exp_f32_e32 v101, v101
	v_exp_f32_e32 v102, v102
	v_exp_f32_e32 v103, v103
	v_cvt_pk_bf16_f32 v208, v96, v97
	v_cvt_pk_bf16_f32 v209, v98, v99
	v_cvt_pk_bf16_f32 v210, v100, v101
	v_cvt_pk_bf16_f32 v211, v102, v103
	v_exp_f32_e32 v104, v104
	v_exp_f32_e32 v105, v105
	s_waitcnt lgkmcnt(6)
	v_mfma_f32_32x32x16_bf16 v[48:63], v[224:227], v[208:211], v[48:63]
	v_exp_f32_e32 v106, v106
	v_exp_f32_e32 v107, v107
	v_exp_f32_e32 v108, v108
	ds_read_b64_tr_b16 v[136:137], v178 offset:4096
	ds_read_b64_tr_b16 v[138:139], v179 offset:6144
	v_mfma_f32_32x32x16_bf16 v[32:47], v[228:231], v[208:211], v[32:47]
	v_exp_f32_e32 v109, v109
	v_exp_f32_e32 v110, v110
	v_exp_f32_e32 v111, v111
	ds_read_b64_tr_b16 v[144:145], v174 offset:8192
	ds_read_b64_tr_b16 v[146:147], v175 offset:10240
	v_mfma_f32_32x32x16_bf16 v[16:31], v[232:235], v[208:211], v[16:31]
	v_cvt_pk_bf16_f32 v212, v104, v105
	v_cvt_pk_bf16_f32 v213, v106, v107
	v_cvt_pk_bf16_f32 v214, v108, v109
	v_cvt_pk_bf16_f32 v215, v110, v111
	v_add_f32_e32 v187, v96, v187
	v_add_f32_e32 v192, v97, v192
	ds_read_b64_tr_b16 v[148:149], v176 offset:8192
	ds_read_b64_tr_b16 v[150:151], v177 offset:10240
	v_mfma_f32_32x32x16_bf16 v[0:15], v[236:239], v[208:211], v[0:15]
	v_add_f32_e32 v193, v98, v193
	v_add_f32_e32 v194, v99, v194
	v_add_f32_e32 v187, v100, v187
	v_add_f32_e32 v192, v101, v192
	v_add_f32_e32 v193, v102, v193
	v_add_f32_e32 v194, v103, v194
	ds_read_b64_tr_b16 v[152:153], v178 offset:8192
	ds_read_b64_tr_b16 v[154:155], v179 offset:10240
	s_waitcnt lgkmcnt(6)
	v_mfma_f32_32x32x16_bf16 v[48:63], v[128:131], v[212:215], v[48:63]
	v_exp_f32_e32 v80, v80
	v_exp_f32_e32 v81, v81
	v_exp_f32_e32 v82, v82
	ds_read_b64_tr_b16 v[240:241], v183 offset:8192
	ds_read_b64_tr_b16 v[242:243], v184 offset:10240
	v_mfma_f32_32x32x16_bf16 v[32:47], v[132:135], v[212:215], v[32:47]
	v_exp_f32_e32 v83, v83
	v_exp_f32_e32 v84, v84
	v_exp_f32_e32 v85, v85
	ds_read_b64_tr_b16 v[196:197], v174 offset:12288
	ds_read_b64_tr_b16 v[198:199], v175 offset:14336
	v_mfma_f32_32x32x16_bf16 v[16:31], v[136:139], v[212:215], v[16:31]
	v_exp_f32_e32 v86, v86
	v_exp_f32_e32 v87, v87
	v_cvt_pk_bf16_f32 v216, v80, v81
	v_cvt_pk_bf16_f32 v217, v82, v83
	ds_read_b64_tr_b16 v[200:201], v176 offset:12288
	ds_read_b64_tr_b16 v[202:203], v177 offset:14336
	v_mfma_f32_32x32x16_bf16 v[0:15], v[140:143], v[212:215], v[0:15]
	v_cvt_pk_bf16_f32 v218, v84, v85
	v_cvt_pk_bf16_f32 v219, v86, v87
	v_add_f32_e32 v187, v104, v187
	v_add_f32_e32 v192, v105, v192
	v_add_f32_e32 v193, v106, v193
	v_add_f32_e32 v194, v107, v194
	ds_read_b64_tr_b16 v[204:205], v178 offset:12288
	ds_read_b64_tr_b16 v[206:207], v179 offset:14336
	s_waitcnt lgkmcnt(6)
	v_mfma_f32_32x32x16_bf16 v[48:63], v[144:147], v[216:219], v[48:63]
	v_exp_f32_e32 v88, v88
	v_exp_f32_e32 v89, v89
	v_exp_f32_e32 v90, v90
	ds_read_b64_tr_b16 v[246:247], v183 offset:12288
	ds_read_b64_tr_b16 v[248:249], v184 offset:14336
	v_mfma_f32_32x32x16_bf16 v[32:47], v[148:151], v[216:219], v[32:47]
	v_exp_f32_e32 v91, v91
	v_exp_f32_e32 v92, v92
	v_exp_f32_e32 v93, v93
	ds_read_b128 v[128:131], v188 offset:24576
	v_mfma_f32_32x32x16_bf16 v[16:31], v[152:155], v[216:219], v[16:31]
	v_exp_f32_e32 v94, v94
	v_exp_f32_e32 v95, v95
	v_cvt_pk_bf16_f32 v220, v88, v89
	v_cvt_pk_bf16_f32 v221, v90, v91
	ds_read_b128 v[132:135], v189 offset:16384
	v_mfma_f32_32x32x16_bf16 v[0:15], v[240:243], v[216:219], v[0:15]
	v_cvt_pk_bf16_f32 v222, v92, v93
	v_cvt_pk_bf16_f32 v223, v94, v95
	v_add_f32_e32 v187, v108, v187
	v_add_f32_e32 v192, v109, v192
	v_add_f32_e32 v193, v110, v193
	v_add_f32_e32 v194, v111, v194
	ds_read_b128 v[136:139], v189 offset:24576
	s_waitcnt lgkmcnt(3)
	v_mfma_f32_32x32x16_bf16 v[48:63], v[196:199], v[220:223], v[48:63]
	v_add_f32_e32 v187, v80, v187
	v_add_f32_e32 v192, v81, v192
	v_add_f32_e32 v193, v82, v193
	v_add_f32_e32 v194, v83, v194
	v_add_f32_e32 v187, v84, v187
	v_add_f32_e32 v192, v85, v192
	ds_read_b128 v[140:143], v190 offset:16384
	ds_read_b128 v[144:147], v190 offset:24576
	v_mfma_f32_32x32x16_bf16 v[32:47], v[200:203], v[220:223], v[32:47]
	v_add_f32_e32 v193, v86, v193
	v_add_f32_e32 v194, v87, v194
	v_add_f32_e32 v187, v88, v187
	v_add_f32_e32 v192, v89, v192
	v_add_f32_e32 v193, v90, v193
	v_add_f32_e32 v194, v91, v194
	ds_read_b128 v[148:151], v191 offset:16384
	v_mfma_f32_32x32x16_bf16 v[16:31], v[204:207], v[220:223], v[16:31]
	v_add_f32_e32 v187, v92, v187
	v_add_f32_e32 v192, v93, v192
	v_add_f32_e32 v193, v94, v193
	v_add_f32_e32 v194, v95, v194
	ds_read_b128 v[152:155], v191 offset:24576
	ds_read_b128 v[80:83], v188 offset:16384
	v_mfma_f32_32x32x16_bf16 v[0:15], v[246:249], v[220:223], v[0:15]
	s_waitcnt vmcnt(4)
	s_waitcnt lgkmcnt(0)
	s_barrier
	s_add_i32 s10, s68, -3
	s_min_u32 s10, s10, s24
	s_lshl_b32 s10, s10, 15
	s_add_u32 s22, s20, s10
	s_addc_u32 s23, s21, 0
	ds_read_b64_tr_b16 v[224:225], v174 offset:16384
	ds_read_b64_tr_b16 v[226:227], v175 offset:18432
	ds_read_b64_tr_b16 v[228:229], v176 offset:16384
	ds_read_b64_tr_b16 v[230:231], v177 offset:18432
	ds_read_b64_tr_b16 v[232:233], v178 offset:16384
	ds_read_b64_tr_b16 v[234:235], v179 offset:18432
	ds_read_b64_tr_b16 v[236:237], v183 offset:16384
	ds_read_b64_tr_b16 v[238:239], v184 offset:18432
	s_mov_b32 m0, s43
	v_mfma_f32_32x32x16_bf16 v[96:111], v[80:83], v[112:115], v[64:79]
	global_load_lds_dwordx4 v163, s[22:23]
	s_mov_b32 m0, s45
	v_mfma_f32_32x32x16_bf16 v[96:111], v[132:135], v[116:119], v[96:111]
	global_load_lds_dwordx4 v254, s[22:23]
	s_mov_b32 m0, s25
	v_mfma_f32_32x32x16_bf16 v[96:111], v[140:143], v[120:123], v[96:111]
	global_load_lds_dwordx4 v255, s[4:5]
	ds_read_b64_tr_b16 v[132:133], v176 offset:20480
	ds_read_b64_tr_b16 v[134:135], v177 offset:22528
	s_mov_b32 m0, s63
	v_mfma_f32_32x32x16_bf16 v[96:111], v[148:151], v[124:127], v[96:111]
	global_load_lds_dwordx4 v253, s[4:5]
	ds_read_b64_tr_b16 v[140:141], v183 offset:20480
	ds_read_b64_tr_b16 v[142:143], v184 offset:22528
	v_mfma_f32_32x32x16_bf16 v[80:95], v[128:131], v[112:115], v[64:79]
	ds_read_b64_tr_b16 v[128:129], v174 offset:20480
	ds_read_b64_tr_b16 v[130:131], v175 offset:22528
	v_mfma_f32_32x32x16_bf16 v[80:95], v[136:139], v[116:119], v[80:95]
	s_nop 3
	v_mfma_f32_32x32x16_bf16 v[80:95], v[144:147], v[120:123], v[80:95]
	v_exp_f32_e32 v96, v96
	v_exp_f32_e32 v97, v97
	v_exp_f32_e32 v98, v98
	v_mfma_f32_32x32x16_bf16 v[80:95], v[152:155], v[124:127], v[80:95]
	v_exp_f32_e32 v99, v99
	v_exp_f32_e32 v100, v100
	v_exp_f32_e32 v101, v101
	v_exp_f32_e32 v102, v102
	v_exp_f32_e32 v103, v103
	v_cvt_pk_bf16_f32 v208, v96, v97
	v_cvt_pk_bf16_f32 v209, v98, v99
	v_cvt_pk_bf16_f32 v210, v100, v101
	v_cvt_pk_bf16_f32 v211, v102, v103
	v_exp_f32_e32 v104, v104
	v_exp_f32_e32 v105, v105
	s_waitcnt lgkmcnt(6)
	v_mfma_f32_32x32x16_bf16 v[48:63], v[224:227], v[208:211], v[48:63]
	v_exp_f32_e32 v106, v106
	v_exp_f32_e32 v107, v107
	v_exp_f32_e32 v108, v108
	ds_read_b64_tr_b16 v[136:137], v178 offset:20480
	ds_read_b64_tr_b16 v[138:139], v179 offset:22528
	v_mfma_f32_32x32x16_bf16 v[32:47], v[228:231], v[208:211], v[32:47]
	v_exp_f32_e32 v109, v109
	v_exp_f32_e32 v110, v110
	v_exp_f32_e32 v111, v111
	ds_read_b64_tr_b16 v[144:145], v174 offset:24576
	ds_read_b64_tr_b16 v[146:147], v175 offset:26624
	v_mfma_f32_32x32x16_bf16 v[16:31], v[232:235], v[208:211], v[16:31]
	v_cvt_pk_bf16_f32 v212, v104, v105
	v_cvt_pk_bf16_f32 v213, v106, v107
	v_cvt_pk_bf16_f32 v214, v108, v109
	v_cvt_pk_bf16_f32 v215, v110, v111
	v_add_f32_e32 v187, v96, v187
	v_add_f32_e32 v192, v97, v192
	ds_read_b64_tr_b16 v[148:149], v176 offset:24576
	ds_read_b64_tr_b16 v[150:151], v177 offset:26624
	v_mfma_f32_32x32x16_bf16 v[0:15], v[236:239], v[208:211], v[0:15]
	v_add_f32_e32 v193, v98, v193
	v_add_f32_e32 v194, v99, v194
	v_add_f32_e32 v187, v100, v187
	v_add_f32_e32 v192, v101, v192
	v_add_f32_e32 v193, v102, v193
	v_add_f32_e32 v194, v103, v194
	ds_read_b64_tr_b16 v[152:153], v178 offset:24576
	ds_read_b64_tr_b16 v[154:155], v179 offset:26624
	s_waitcnt lgkmcnt(6)
	v_mfma_f32_32x32x16_bf16 v[48:63], v[128:131], v[212:215], v[48:63]
	v_exp_f32_e32 v80, v80
	v_exp_f32_e32 v81, v81
	v_exp_f32_e32 v82, v82
	ds_read_b64_tr_b16 v[240:241], v183 offset:24576
	ds_read_b64_tr_b16 v[242:243], v184 offset:26624
	v_mfma_f32_32x32x16_bf16 v[32:47], v[132:135], v[212:215], v[32:47]
	v_exp_f32_e32 v83, v83
	v_exp_f32_e32 v84, v84
	v_exp_f32_e32 v85, v85
	ds_read_b64_tr_b16 v[196:197], v174 offset:28672
	ds_read_b64_tr_b16 v[198:199], v175 offset:30720
	v_mfma_f32_32x32x16_bf16 v[16:31], v[136:139], v[212:215], v[16:31]
	v_exp_f32_e32 v86, v86
	v_exp_f32_e32 v87, v87
	v_cvt_pk_bf16_f32 v216, v80, v81
	v_cvt_pk_bf16_f32 v217, v82, v83
	ds_read_b64_tr_b16 v[200:201], v176 offset:28672
	ds_read_b64_tr_b16 v[202:203], v177 offset:30720
	v_mfma_f32_32x32x16_bf16 v[0:15], v[140:143], v[212:215], v[0:15]
	v_cvt_pk_bf16_f32 v218, v84, v85
	v_cvt_pk_bf16_f32 v219, v86, v87
	v_add_f32_e32 v187, v104, v187
	v_add_f32_e32 v192, v105, v192
	v_add_f32_e32 v193, v106, v193
	v_add_f32_e32 v194, v107, v194
	ds_read_b64_tr_b16 v[204:205], v178 offset:28672
	ds_read_b64_tr_b16 v[206:207], v179 offset:30720
	s_waitcnt lgkmcnt(6)
	v_mfma_f32_32x32x16_bf16 v[48:63], v[144:147], v[216:219], v[48:63]
	v_exp_f32_e32 v88, v88
	v_exp_f32_e32 v89, v89
	v_exp_f32_e32 v90, v90
	ds_read_b64_tr_b16 v[246:247], v183 offset:28672
	ds_read_b64_tr_b16 v[248:249], v184 offset:30720
	v_mfma_f32_32x32x16_bf16 v[32:47], v[148:151], v[216:219], v[32:47]
	v_exp_f32_e32 v91, v91
	v_exp_f32_e32 v92, v92
	v_exp_f32_e32 v93, v93
	ds_read_b128 v[128:131], v188 offset:40960
	v_mfma_f32_32x32x16_bf16 v[16:31], v[152:155], v[216:219], v[16:31]
	v_exp_f32_e32 v94, v94
	v_exp_f32_e32 v95, v95
	v_cvt_pk_bf16_f32 v220, v88, v89
	v_cvt_pk_bf16_f32 v221, v90, v91
	ds_read_b128 v[132:135], v189 offset:32768
	v_mfma_f32_32x32x16_bf16 v[0:15], v[240:243], v[216:219], v[0:15]
	v_cvt_pk_bf16_f32 v222, v92, v93
	v_cvt_pk_bf16_f32 v223, v94, v95
	v_add_f32_e32 v187, v108, v187
	v_add_f32_e32 v192, v109, v192
	v_add_f32_e32 v193, v110, v193
	v_add_f32_e32 v194, v111, v194
	ds_read_b128 v[136:139], v189 offset:40960
	s_waitcnt lgkmcnt(3)
	v_mfma_f32_32x32x16_bf16 v[48:63], v[196:199], v[220:223], v[48:63]
	v_add_f32_e32 v187, v80, v187
	v_add_f32_e32 v192, v81, v192
	v_add_f32_e32 v193, v82, v193
	v_add_f32_e32 v194, v83, v194
	v_add_f32_e32 v187, v84, v187
	v_add_f32_e32 v192, v85, v192
	ds_read_b128 v[140:143], v190 offset:32768
	ds_read_b128 v[144:147], v190 offset:40960
	v_mfma_f32_32x32x16_bf16 v[32:47], v[200:203], v[220:223], v[32:47]
	v_add_f32_e32 v193, v86, v193
	v_add_f32_e32 v194, v87, v194
	v_add_f32_e32 v187, v88, v187
	v_add_f32_e32 v192, v89, v192
	v_add_f32_e32 v193, v90, v193
	v_add_f32_e32 v194, v91, v194
	ds_read_b128 v[148:151], v191 offset:32768
	v_mfma_f32_32x32x16_bf16 v[16:31], v[204:207], v[220:223], v[16:31]
	v_add_f32_e32 v187, v92, v187
	v_add_f32_e32 v192, v93, v192
	v_add_f32_e32 v193, v94, v193
	v_add_f32_e32 v194, v95, v194
	ds_read_b128 v[152:155], v191 offset:40960
	ds_read_b128 v[80:83], v188 offset:32768
	v_mfma_f32_32x32x16_bf16 v[0:15], v[246:249], v[220:223], v[0:15]
	s_waitcnt vmcnt(4)
	s_waitcnt lgkmcnt(0)
	s_barrier
	s_add_i32 s10, s68, -2
	s_min_u32 s10, s10, s24
	s_lshl_b32 s10, s10, 15
	s_add_u32 s4, s20, s10
	s_addc_u32 s5, s21, 0
	ds_read_b64_tr_b16 v[224:225], v174 offset:32768
	ds_read_b64_tr_b16 v[226:227], v175 offset:34816
	ds_read_b64_tr_b16 v[228:229], v176 offset:32768
	ds_read_b64_tr_b16 v[230:231], v177 offset:34816
	ds_read_b64_tr_b16 v[232:233], v178 offset:32768
	ds_read_b64_tr_b16 v[234:235], v179 offset:34816
	ds_read_b64_tr_b16 v[236:237], v183 offset:32768
	ds_read_b64_tr_b16 v[238:239], v184 offset:34816
	s_mov_b32 m0, s46
	v_mfma_f32_32x32x16_bf16 v[96:111], v[80:83], v[112:115], v[64:79]
	global_load_lds_dwordx4 v163, s[4:5]
	s_mov_b32 m0, s47
	v_mfma_f32_32x32x16_bf16 v[96:111], v[132:135], v[116:119], v[96:111]
	global_load_lds_dwordx4 v254, s[4:5]
	s_mov_b32 m0, s44
	v_mfma_f32_32x32x16_bf16 v[96:111], v[140:143], v[120:123], v[96:111]
	global_load_lds_dwordx4 v255, s[22:23]
	ds_read_b64_tr_b16 v[132:133], v176 offset:36864
	ds_read_b64_tr_b16 v[134:135], v177 offset:38912
	s_mov_b32 m0, s48
	v_mfma_f32_32x32x16_bf16 v[96:111], v[148:151], v[124:127], v[96:111]
	global_load_lds_dwordx4 v253, s[22:23]
	ds_read_b64_tr_b16 v[140:141], v183 offset:36864
	ds_read_b64_tr_b16 v[142:143], v184 offset:38912
	v_mfma_f32_32x32x16_bf16 v[80:95], v[128:131], v[112:115], v[64:79]
	ds_read_b64_tr_b16 v[128:129], v174 offset:36864
	ds_read_b64_tr_b16 v[130:131], v175 offset:38912
	v_mfma_f32_32x32x16_bf16 v[80:95], v[136:139], v[116:119], v[80:95]
	s_nop 3
	v_mfma_f32_32x32x16_bf16 v[80:95], v[144:147], v[120:123], v[80:95]
	v_exp_f32_e32 v96, v96
	v_exp_f32_e32 v97, v97
	v_exp_f32_e32 v98, v98
	v_mfma_f32_32x32x16_bf16 v[80:95], v[152:155], v[124:127], v[80:95]
	v_exp_f32_e32 v99, v99
	v_exp_f32_e32 v100, v100
	v_exp_f32_e32 v101, v101
	v_exp_f32_e32 v102, v102
	v_exp_f32_e32 v103, v103
	v_cvt_pk_bf16_f32 v208, v96, v97
	v_cvt_pk_bf16_f32 v209, v98, v99
	v_cvt_pk_bf16_f32 v210, v100, v101
	v_cvt_pk_bf16_f32 v211, v102, v103
	v_exp_f32_e32 v104, v104
	v_exp_f32_e32 v105, v105
	s_waitcnt lgkmcnt(6)
	v_mfma_f32_32x32x16_bf16 v[48:63], v[224:227], v[208:211], v[48:63]
	v_exp_f32_e32 v106, v106
	v_exp_f32_e32 v107, v107
	v_exp_f32_e32 v108, v108
	ds_read_b64_tr_b16 v[136:137], v178 offset:36864
	ds_read_b64_tr_b16 v[138:139], v179 offset:38912
	v_mfma_f32_32x32x16_bf16 v[32:47], v[228:231], v[208:211], v[32:47]
	v_exp_f32_e32 v109, v109
	v_exp_f32_e32 v110, v110
	v_exp_f32_e32 v111, v111
	ds_read_b64_tr_b16 v[144:145], v174 offset:40960
	ds_read_b64_tr_b16 v[146:147], v175 offset:43008
	v_mfma_f32_32x32x16_bf16 v[16:31], v[232:235], v[208:211], v[16:31]
	v_cvt_pk_bf16_f32 v212, v104, v105
	v_cvt_pk_bf16_f32 v213, v106, v107
	v_cvt_pk_bf16_f32 v214, v108, v109
	v_cvt_pk_bf16_f32 v215, v110, v111
	v_add_f32_e32 v187, v96, v187
	v_add_f32_e32 v192, v97, v192
	ds_read_b64_tr_b16 v[148:149], v176 offset:40960
	ds_read_b64_tr_b16 v[150:151], v177 offset:43008
	v_mfma_f32_32x32x16_bf16 v[0:15], v[236:239], v[208:211], v[0:15]
	v_add_f32_e32 v193, v98, v193
	v_add_f32_e32 v194, v99, v194
	v_add_f32_e32 v187, v100, v187
	v_add_f32_e32 v192, v101, v192
	v_add_f32_e32 v193, v102, v193
	v_add_f32_e32 v194, v103, v194
	ds_read_b64_tr_b16 v[152:153], v178 offset:40960
	ds_read_b64_tr_b16 v[154:155], v179 offset:43008
	s_waitcnt lgkmcnt(6)
	v_mfma_f32_32x32x16_bf16 v[48:63], v[128:131], v[212:215], v[48:63]
	v_exp_f32_e32 v80, v80
	v_exp_f32_e32 v81, v81
	v_exp_f32_e32 v82, v82
	ds_read_b64_tr_b16 v[240:241], v183 offset:40960
	ds_read_b64_tr_b16 v[242:243], v184 offset:43008
	v_mfma_f32_32x32x16_bf16 v[32:47], v[132:135], v[212:215], v[32:47]
	v_exp_f32_e32 v83, v83
	v_exp_f32_e32 v84, v84
	v_exp_f32_e32 v85, v85
	ds_read_b64_tr_b16 v[196:197], v174 offset:45056
	ds_read_b64_tr_b16 v[198:199], v175 offset:47104
	v_mfma_f32_32x32x16_bf16 v[16:31], v[136:139], v[212:215], v[16:31]
	v_exp_f32_e32 v86, v86
	v_exp_f32_e32 v87, v87
	v_cvt_pk_bf16_f32 v216, v80, v81
	v_cvt_pk_bf16_f32 v217, v82, v83
	ds_read_b64_tr_b16 v[200:201], v176 offset:45056
	ds_read_b64_tr_b16 v[202:203], v177 offset:47104
	v_mfma_f32_32x32x16_bf16 v[0:15], v[140:143], v[212:215], v[0:15]
	v_cvt_pk_bf16_f32 v218, v84, v85
	v_cvt_pk_bf16_f32 v219, v86, v87
	v_add_f32_e32 v187, v104, v187
	v_add_f32_e32 v192, v105, v192
	v_add_f32_e32 v193, v106, v193
	v_add_f32_e32 v194, v107, v194
	ds_read_b64_tr_b16 v[204:205], v178 offset:45056
	ds_read_b64_tr_b16 v[206:207], v179 offset:47104
	s_waitcnt lgkmcnt(6)
	v_mfma_f32_32x32x16_bf16 v[48:63], v[144:147], v[216:219], v[48:63]
	v_exp_f32_e32 v88, v88
	v_exp_f32_e32 v89, v89
	v_exp_f32_e32 v90, v90
	ds_read_b64_tr_b16 v[246:247], v183 offset:45056
	ds_read_b64_tr_b16 v[248:249], v184 offset:47104
	v_mfma_f32_32x32x16_bf16 v[32:47], v[148:151], v[216:219], v[32:47]
	v_exp_f32_e32 v91, v91
	v_exp_f32_e32 v92, v92
	v_exp_f32_e32 v93, v93
	ds_read_b128 v[128:131], v188 offset:57344
	v_mfma_f32_32x32x16_bf16 v[16:31], v[152:155], v[216:219], v[16:31]
	v_exp_f32_e32 v94, v94
	v_exp_f32_e32 v95, v95
	v_cvt_pk_bf16_f32 v220, v88, v89
	v_cvt_pk_bf16_f32 v221, v90, v91
	ds_read_b128 v[132:135], v189 offset:49152
	v_mfma_f32_32x32x16_bf16 v[0:15], v[240:243], v[216:219], v[0:15]
	v_cvt_pk_bf16_f32 v222, v92, v93
	v_cvt_pk_bf16_f32 v223, v94, v95
	v_add_f32_e32 v187, v108, v187
	v_add_f32_e32 v192, v109, v192
	v_add_f32_e32 v193, v110, v193
	v_add_f32_e32 v194, v111, v194
	ds_read_b128 v[136:139], v189 offset:57344
	s_waitcnt lgkmcnt(3)
	v_mfma_f32_32x32x16_bf16 v[48:63], v[196:199], v[220:223], v[48:63]
	v_add_f32_e32 v187, v80, v187
	v_add_f32_e32 v192, v81, v192
	v_add_f32_e32 v193, v82, v193
	v_add_f32_e32 v194, v83, v194
	v_add_f32_e32 v187, v84, v187
	v_add_f32_e32 v192, v85, v192
	ds_read_b128 v[140:143], v190 offset:49152
	ds_read_b128 v[144:147], v190 offset:57344
	v_mfma_f32_32x32x16_bf16 v[32:47], v[200:203], v[220:223], v[32:47]
	v_add_f32_e32 v193, v86, v193
	v_add_f32_e32 v194, v87, v194
	v_add_f32_e32 v187, v88, v187
	v_add_f32_e32 v192, v89, v192
	v_add_f32_e32 v193, v90, v193
	v_add_f32_e32 v194, v91, v194
	ds_read_b128 v[148:151], v191 offset:49152
	v_mfma_f32_32x32x16_bf16 v[16:31], v[204:207], v[220:223], v[16:31]
	v_add_f32_e32 v187, v92, v187
	v_add_f32_e32 v192, v93, v192
	v_add_f32_e32 v193, v94, v193
	v_add_f32_e32 v194, v95, v194
	ds_read_b128 v[152:155], v191 offset:57344
	ds_read_b128 v[80:83], v188 offset:49152
	v_mfma_f32_32x32x16_bf16 v[0:15], v[246:249], v[220:223], v[0:15]
	s_waitcnt vmcnt(4)
	s_waitcnt lgkmcnt(0)
	s_barrier
	s_add_i32 s10, s68, -1
	s_min_u32 s10, s10, s24
	s_lshl_b32 s10, s10, 15
	s_add_u32 s22, s20, s10
	s_addc_u32 s23, s21, 0
	ds_read_b64_tr_b16 v[224:225], v174 offset:49152
	ds_read_b64_tr_b16 v[226:227], v175 offset:51200
	ds_read_b64_tr_b16 v[228:229], v176 offset:49152
	ds_read_b64_tr_b16 v[230:231], v177 offset:51200
	ds_read_b64_tr_b16 v[232:233], v178 offset:49152
	ds_read_b64_tr_b16 v[234:235], v179 offset:51200
	ds_read_b64_tr_b16 v[236:237], v183 offset:49152
	ds_read_b64_tr_b16 v[238:239], v184 offset:51200
	s_mov_b32 m0, s49
	v_mfma_f32_32x32x16_bf16 v[96:111], v[80:83], v[112:115], v[64:79]
	global_load_lds_dwordx4 v163, s[22:23]
	s_mov_b32 m0, s50
	v_mfma_f32_32x32x16_bf16 v[96:111], v[132:135], v[116:119], v[96:111]
	global_load_lds_dwordx4 v254, s[22:23]
	s_mov_b32 m0, s51
	v_mfma_f32_32x32x16_bf16 v[96:111], v[140:143], v[120:123], v[96:111]
	global_load_lds_dwordx4 v255, s[4:5]
	ds_read_b64_tr_b16 v[132:133], v176 offset:53248
	ds_read_b64_tr_b16 v[134:135], v177 offset:55296
	s_mov_b32 m0, s52
	v_mfma_f32_32x32x16_bf16 v[96:111], v[148:151], v[124:127], v[96:111]
	global_load_lds_dwordx4 v253, s[4:5]
	ds_read_b64_tr_b16 v[140:141], v183 offset:53248
	ds_read_b64_tr_b16 v[142:143], v184 offset:55296
	v_mfma_f32_32x32x16_bf16 v[80:95], v[128:131], v[112:115], v[64:79]
	ds_read_b64_tr_b16 v[128:129], v174 offset:53248
	ds_read_b64_tr_b16 v[130:131], v175 offset:55296
	v_mfma_f32_32x32x16_bf16 v[80:95], v[136:139], v[116:119], v[80:95]
	s_nop 3
	v_mfma_f32_32x32x16_bf16 v[80:95], v[144:147], v[120:123], v[80:95]
	v_exp_f32_e32 v96, v96
	v_exp_f32_e32 v97, v97
	v_exp_f32_e32 v98, v98
	v_mfma_f32_32x32x16_bf16 v[80:95], v[152:155], v[124:127], v[80:95]
	v_exp_f32_e32 v99, v99
	v_exp_f32_e32 v100, v100
	v_exp_f32_e32 v101, v101
	v_exp_f32_e32 v102, v102
	v_exp_f32_e32 v103, v103
	v_cvt_pk_bf16_f32 v208, v96, v97
	v_cvt_pk_bf16_f32 v209, v98, v99
	v_cvt_pk_bf16_f32 v210, v100, v101
	v_cvt_pk_bf16_f32 v211, v102, v103
	v_exp_f32_e32 v104, v104
	v_exp_f32_e32 v105, v105
	s_waitcnt lgkmcnt(6)
	v_mfma_f32_32x32x16_bf16 v[48:63], v[224:227], v[208:211], v[48:63]
	v_exp_f32_e32 v106, v106
	v_exp_f32_e32 v107, v107
	v_exp_f32_e32 v108, v108
	ds_read_b64_tr_b16 v[136:137], v178 offset:53248
	ds_read_b64_tr_b16 v[138:139], v179 offset:55296
	v_mfma_f32_32x32x16_bf16 v[32:47], v[228:231], v[208:211], v[32:47]
	v_exp_f32_e32 v109, v109
	v_exp_f32_e32 v110, v110
	v_exp_f32_e32 v111, v111
	ds_read_b64_tr_b16 v[144:145], v174 offset:57344
	ds_read_b64_tr_b16 v[146:147], v175 offset:59392
	v_mfma_f32_32x32x16_bf16 v[16:31], v[232:235], v[208:211], v[16:31]
	v_cvt_pk_bf16_f32 v212, v104, v105
	v_cvt_pk_bf16_f32 v213, v106, v107
	v_cvt_pk_bf16_f32 v214, v108, v109
	v_cvt_pk_bf16_f32 v215, v110, v111
	v_add_f32_e32 v187, v96, v187
	v_add_f32_e32 v192, v97, v192
	ds_read_b64_tr_b16 v[148:149], v176 offset:57344
	ds_read_b64_tr_b16 v[150:151], v177 offset:59392
	v_mfma_f32_32x32x16_bf16 v[0:15], v[236:239], v[208:211], v[0:15]
	v_add_f32_e32 v193, v98, v193
	v_add_f32_e32 v194, v99, v194
	v_add_f32_e32 v187, v100, v187
	v_add_f32_e32 v192, v101, v192
	v_add_f32_e32 v193, v102, v193
	v_add_f32_e32 v194, v103, v194
	ds_read_b64_tr_b16 v[152:153], v178 offset:57344
	ds_read_b64_tr_b16 v[154:155], v179 offset:59392
	s_waitcnt lgkmcnt(6)
	v_mfma_f32_32x32x16_bf16 v[48:63], v[128:131], v[212:215], v[48:63]
	v_exp_f32_e32 v80, v80
	v_exp_f32_e32 v81, v81
	v_exp_f32_e32 v82, v82
	ds_read_b64_tr_b16 v[240:241], v183 offset:57344
	ds_read_b64_tr_b16 v[242:243], v184 offset:59392
	v_mfma_f32_32x32x16_bf16 v[32:47], v[132:135], v[212:215], v[32:47]
	v_exp_f32_e32 v83, v83
	v_exp_f32_e32 v84, v84
	v_exp_f32_e32 v85, v85
	ds_read_b64_tr_b16 v[196:197], v174 offset:61440
	ds_read_b64_tr_b16 v[198:199], v175 offset:63488
	v_mfma_f32_32x32x16_bf16 v[16:31], v[136:139], v[212:215], v[16:31]
	v_exp_f32_e32 v86, v86
	v_exp_f32_e32 v87, v87
	v_cvt_pk_bf16_f32 v216, v80, v81
	v_cvt_pk_bf16_f32 v217, v82, v83
	ds_read_b64_tr_b16 v[200:201], v176 offset:61440
	ds_read_b64_tr_b16 v[202:203], v177 offset:63488
	v_mfma_f32_32x32x16_bf16 v[0:15], v[140:143], v[212:215], v[0:15]
	v_cvt_pk_bf16_f32 v218, v84, v85
	v_cvt_pk_bf16_f32 v219, v86, v87
	v_add_f32_e32 v187, v104, v187
	v_add_f32_e32 v192, v105, v192
	v_add_f32_e32 v193, v106, v193
	v_add_f32_e32 v194, v107, v194
	ds_read_b64_tr_b16 v[204:205], v178 offset:61440
	ds_read_b64_tr_b16 v[206:207], v179 offset:63488
	s_waitcnt lgkmcnt(6)
	v_mfma_f32_32x32x16_bf16 v[48:63], v[144:147], v[216:219], v[48:63]
	v_exp_f32_e32 v88, v88
	v_exp_f32_e32 v89, v89
	v_exp_f32_e32 v90, v90
	ds_read_b64_tr_b16 v[246:247], v183 offset:61440
	ds_read_b64_tr_b16 v[248:249], v184 offset:63488
	v_mfma_f32_32x32x16_bf16 v[32:47], v[148:151], v[216:219], v[32:47]
	v_exp_f32_e32 v91, v91
	v_exp_f32_e32 v92, v92
	v_exp_f32_e32 v93, v93
	ds_read_b128 v[128:131], v188 offset:8192
	v_mfma_f32_32x32x16_bf16 v[16:31], v[152:155], v[216:219], v[16:31]
	v_exp_f32_e32 v94, v94
	v_exp_f32_e32 v95, v95
	v_cvt_pk_bf16_f32 v220, v88, v89
	v_cvt_pk_bf16_f32 v221, v90, v91
	ds_read_b128 v[132:135], v189
	v_mfma_f32_32x32x16_bf16 v[0:15], v[240:243], v[216:219], v[0:15]
	v_cvt_pk_bf16_f32 v222, v92, v93
	v_cvt_pk_bf16_f32 v223, v94, v95
	v_add_f32_e32 v187, v108, v187
	v_add_f32_e32 v192, v109, v192
	v_add_f32_e32 v193, v110, v193
	v_add_f32_e32 v194, v111, v194
	ds_read_b128 v[136:139], v189 offset:8192
	s_waitcnt lgkmcnt(3)
	v_mfma_f32_32x32x16_bf16 v[48:63], v[196:199], v[220:223], v[48:63]
	v_add_f32_e32 v187, v80, v187
	v_add_f32_e32 v192, v81, v192
	v_add_f32_e32 v193, v82, v193
	v_add_f32_e32 v194, v83, v194
	v_add_f32_e32 v187, v84, v187
	v_add_f32_e32 v192, v85, v192
	ds_read_b128 v[140:143], v190
	ds_read_b128 v[144:147], v190 offset:8192
	v_mfma_f32_32x32x16_bf16 v[32:47], v[200:203], v[220:223], v[32:47]
	v_add_f32_e32 v193, v86, v193
	v_add_f32_e32 v194, v87, v194
	v_add_f32_e32 v187, v88, v187
	v_add_f32_e32 v192, v89, v192
	v_add_f32_e32 v193, v90, v193
	v_add_f32_e32 v194, v91, v194
	ds_read_b128 v[148:151], v191
	v_mfma_f32_32x32x16_bf16 v[16:31], v[204:207], v[220:223], v[16:31]
	v_add_f32_e32 v187, v92, v187
	v_add_f32_e32 v192, v93, v192
	v_add_f32_e32 v193, v94, v193
	v_add_f32_e32 v194, v95, v194
	ds_read_b128 v[152:155], v191 offset:8192
	ds_read_b128 v[80:83], v188
	v_mfma_f32_32x32x16_bf16 v[0:15], v[246:249], v[220:223], v[0:15]
	s_waitcnt vmcnt(4)
	s_add_i32 s68, s68, 4
	s_cmp_ge_u32 s69, s42
	s_waitcnt lgkmcnt(0)
	s_barrier
; #define LAS __attribute__((address_space(3)))
; __device__ __forceinline__ void attn_unit(LAS unsigned char* L, bf16_t* QKV, size_t rowbase, int S, int h, int qb, float lam, const float* subln, unsigned* kmax) {
;     ...
;     lsum = (lsum + lsb) + (lsc + lsd);
;     const float inv = 1.f / (lsum + __shfl_xor(lsum, 32));
;     LAS float* X = (LAS float*)L;
;     const int xo = (32 * qblk + r32) * AXP + 4 * hi;
;     if (hd == 1) { const float sc = inv * lam;
; #pragma unroll
;         for (int d = 0; d < 4; ++d)
; #pragma unroll
;             for (int rg = 0; rg < 4; ++rg) *(LAS f32x4*)(X + xo + 32 * d + 8 * rg) = (f32x4){o[d][4 * rg] * sc, o[d][4 * rg + 1] * sc, o[d][4 * rg + 2] * sc, o[d][4 * rg + 3] * sc}; }
	s_cbranch_scc0 .LBB0_927
	s_setprio 0
	v_add_f32_e32 v64, v187, v192
	v_add_f32_e32 v65, v193, v194
	v_add_f32_e32 v64, v64, v65
	ds_bpermute_b32 v65, v156, v64
	s_waitcnt vmcnt(0)
	s_cmp_eq_u32 s40, 1
	s_waitcnt lgkmcnt(0)
	s_barrier
	v_add_f32_e32 v64, v64, v65
	v_div_scale_f32 v65, s[4:5], v64, v64, 1.0
	v_rcp_f32_e32 v66, v65
	s_nop 0
	v_fma_f32 v67, -v65, v66, 1.0
	v_fmac_f32_e32 v66, v67, v66
	v_div_scale_f32 v67, vcc, 1.0, v64, 1.0
	v_mul_f32_e32 v68, v67, v66
	v_fma_f32 v69, -v65, v68, v67
	v_fmac_f32_e32 v68, v69, v66
	v_fma_f32 v65, -v65, v68, v67
	v_div_fmas_f32 v65, v65, v66, v68
	v_div_fixup_f32 v66, v65, v64, 1.0
	v_or_b32_e32 v64, s41, v182
	v_mad_u32_u24 v64, v64, s38, v158
	v_lshl_add_u32 v64, v64, 2, 0
	s_cbranch_scc0 .LBB0_930
	v_mul_f32_e32 v72, v159, v66
	v_pk_mul_f32 v[68:69], v[48:49], v[72:73] op_sel_hi:[1,0]
	v_pk_mul_f32 v[70:71], v[50:51], v[72:73] op_sel_hi:[1,0]
	ds_write_b128 v64, v[68:71]
	v_pk_mul_f32 v[68:69], v[52:53], v[72:73] op_sel_hi:[1,0]
	v_pk_mul_f32 v[70:71], v[54:55], v[72:73] op_sel_hi:[1,0]
	ds_write_b128 v64, v[68:71] offset:32
	v_pk_mul_f32 v[68:69], v[56:57], v[72:73] op_sel_hi:[1,0]
	v_pk_mul_f32 v[70:71], v[58:59], v[72:73] op_sel_hi:[1,0]
	ds_write_b128 v64, v[68:71] offset:64
	v_pk_mul_f32 v[68:69], v[60:61], v[72:73] op_sel_hi:[1,0]
	v_pk_mul_f32 v[70:71], v[62:63], v[72:73] op_sel_hi:[1,0]
	ds_write_b128 v64, v[68:71] offset:96
	v_pk_mul_f32 v[68:69], v[32:33], v[72:73] op_sel_hi:[1,0]
	v_pk_mul_f32 v[70:71], v[34:35], v[72:73] op_sel_hi:[1,0]
	ds_write_b128 v64, v[68:71] offset:128
	v_pk_mul_f32 v[68:69], v[36:37], v[72:73] op_sel_hi:[1,0]
	v_pk_mul_f32 v[70:71], v[38:39], v[72:73] op_sel_hi:[1,0]
	ds_write_b128 v64, v[68:71] offset:160
	v_pk_mul_f32 v[68:69], v[40:41], v[72:73] op_sel_hi:[1,0]
	v_pk_mul_f32 v[70:71], v[42:43], v[72:73] op_sel_hi:[1,0]
	ds_write_b128 v64, v[68:71] offset:192
	v_pk_mul_f32 v[68:69], v[44:45], v[72:73] op_sel_hi:[1,0]
	v_pk_mul_f32 v[70:71], v[46:47], v[72:73] op_sel_hi:[1,0]
	ds_write_b128 v64, v[68:71] offset:224
	v_pk_mul_f32 v[68:69], v[16:17], v[72:73] op_sel_hi:[1,0]
	v_pk_mul_f32 v[70:71], v[18:19], v[72:73] op_sel_hi:[1,0]
	ds_write_b128 v64, v[68:71] offset:256
	v_pk_mul_f32 v[68:69], v[20:21], v[72:73] op_sel_hi:[1,0]
	v_pk_mul_f32 v[70:71], v[22:23], v[72:73] op_sel_hi:[1,0]
	ds_write_b128 v64, v[68:71] offset:288
	v_pk_mul_f32 v[68:69], v[24:25], v[72:73] op_sel_hi:[1,0]
	v_pk_mul_f32 v[70:71], v[26:27], v[72:73] op_sel_hi:[1,0]
	ds_write_b128 v64, v[68:71] offset:320
	v_pk_mul_f32 v[68:69], v[28:29], v[72:73] op_sel_hi:[1,0]
	v_pk_mul_f32 v[70:71], v[30:31], v[72:73] op_sel_hi:[1,0]
	ds_write_b128 v64, v[68:71] offset:352
	v_pk_mul_f32 v[68:69], v[0:1], v[72:73] op_sel_hi:[1,0]
	v_pk_mul_f32 v[70:71], v[2:3], v[72:73] op_sel_hi:[1,0]
	ds_write_b128 v64, v[68:71] offset:384
	v_pk_mul_f32 v[68:69], v[4:5], v[72:73] op_sel_hi:[1,0]
	v_pk_mul_f32 v[70:71], v[6:7], v[72:73] op_sel_hi:[1,0]
	ds_write_b128 v64, v[68:71] offset:416
	v_pk_mul_f32 v[68:69], v[8:9], v[72:73] op_sel_hi:[1,0]
	v_pk_mul_f32 v[70:71], v[10:11], v[72:73] op_sel_hi:[1,0]
	ds_write_b128 v64, v[68:71] offset:448
	v_pk_mul_f32 v[68:69], v[12:13], v[72:73] op_sel_hi:[1,0]
	v_pk_mul_f32 v[70:71], v[14:15], v[72:73] op_sel_hi:[1,0]
	ds_write_b128 v64, v[68:71] offset:480
